# decode-cache block means woven into GEMM1 k-loop at uniform low rate (1 row group per k-step, in-order vmcnt counted waits) + lazy rescale/permlane swap on window, gathered and own-block MoBA far tile
# speedup vs baseline: 1.0845x; 1.0055x over previous
;     ...
;         const int x = blockIdx.x & 7, ntn = x < 7 ? 4 : 3, nb = gridDim.x >> 3, j = blockIdx.x >> 3;
;         const int lim = 128 * ntn, nown = j < lim ? (lim - j + nb - 1) / nb : 0;
;         auto tile_at = [&](int idx, int& tm, int& tn) -> bool {
;             if (idx < nown) { const int s2 = j + idx * nb; tm = s2 / ntn; tn = 4 * x + s2 % ntn; return true; }
;             const int e = j + (idx - nown) * nb;
;             tm = 128; tn = e;
;             return x == 7 && e < 31;
;         };
;         GemmRegs<ALoadBf16> G; bool pre = false;
;         int tm = 0, tn = 0;
;         bool have = tile_at(0, tm, tn);
.LBB0_252:
	s_mov_b32 s98, 0
	s_mov_b32 s99, 0
	s_load_dword s3, s[34:35], 0x10
	s_and_b32 s8, s80, 7
	s_cmp_eq_u32 s8, 7
	s_cselect_b64 s[4:5], -1, 0
	s_and_b64 s[0:1], s[4:5], exec
	s_cselect_b32 s31, 3, 4
	s_waitcnt lgkmcnt(0)
	s_lshr_b32 s0, s3, 16
	s_cmp_lg_u32 s0, 0
	s_cselect_b64 s[0:1], -1, 0
	s_cmp_lg_u64 s[0:1], 0
	s_addc_u32 s0, s2, 0
	s_lshr_b32 s33, s0, 3
	s_lshr_b32 s30, s80, 3
	s_lshl_b32 s0, s31, 7
	s_cmp_ge_u32 s30, s0
	s_mov_b32 s68, 0
	s_cbranch_scc1 .LBB0_254
	v_cvt_f32_u32_e32 v2, s33
	s_not_b32 s1, s30
	s_sub_i32 s2, 0, s33
	s_add_i32 s0, s0, s1
	v_rcp_iflag_f32_e32 v2, v2
	s_add_i32 s0, s0, s33
	s_ashr_i32 s1, s0, 31
	s_abs_i32 s0, s0
	v_mul_f32_e32 v2, 0x4f7ffffe, v2
	v_cvt_u32_f32_e32 v2, v2
	s_nop 0
	v_readfirstlane_b32 s3, v2
	s_mul_i32 s2, s2, s3
	s_mul_hi_u32 s2, s3, s2
	s_add_i32 s3, s3, s2
	s_mul_hi_u32 s2, s0, s3
	s_mul_i32 s3, s2, s33
	s_sub_i32 s0, s0, s3
	s_add_i32 s9, s2, 1
	s_sub_i32 s3, s0, s33
	s_cmp_ge_u32 s0, s33
	s_cselect_b32 s2, s9, s2
	s_cselect_b32 s0, s3, s0
	s_add_i32 s3, s2, 1
	s_cmp_ge_u32 s0, s33
	s_cselect_b32 s0, s3, s2
	s_xor_b32 s0, s0, s1
	s_sub_i32 s68, s0, s1

; DI int opaque(int v) { asm volatile("" : "+v"(v)); return v; }
; DI void kmean_item(const float* __restrict__ base, const int* __restrict__ pt, int b, int n, float* __restrict__ outp, char* sm) {
;     float* scr = (float*)sm;
;     const int t = opaque(threadIdx.x), lane = t & 63, w = t >> 6;
;     f32x4 a0 = {0.f, 0.f, 0.f, 0.f}, a1 = {0.f, 0.f, 0.f, 0.f};
; #pragma unroll
;     for (int hf = 0; hf < 2; ++hf) {
;         const int pos0 = n * 256 + hf * 128;
;         const size_t r0 = pt ? (size_t)pt[b * 64 + (pos0 >> 7)] * 128 : (size_t)b * 8192 + pos0;
;         const float* rp = base + (r0 + w) * 1024 + lane * 4;
; #pragma unroll 4
;         for (int rr = 0; rr < 32; ++rr) {
;             a0 += __builtin_nontemporal_load((const f32x4*)(rp + (size_t)rr * 4096));
;             a1 += __builtin_nontemporal_load((const f32x4*)(rp + (size_t)rr * 4096 + 256));
;         }
;     }
.LBB0_266:
	v_readlane_b32 s58, v254, 8
	s_nop 3
	s_and_b32 s56, s58, 7
	s_mov_b32 s100, 1
	s_cmp_eq_u32 s56, 7
	s_cbranch_scc0 .Lks_r
	s_cmp_lt_u32 s98, 2
	s_cselect_b32 s100, 2, 1
.Lks_r:
	s_cmpk_lt_u32 s99, 0x80
	s_cselect_b32 s100, s100, 0
	s_add_i32 s98, s98, 1
	s_cmp_eq_u32 s100, 0
	s_cbranch_scc1 .Lks_done
	s_lshr_b32 s56, s99, 6
	s_lshl_b32 s56, s56, 9
	s_add_i32 s101, s58, s56
	s_lshr_b32 s57, s101, 5
	s_and_b32 s56, s101, 31
	s_lshl_b32 s57, s57, 6
	s_lshl_b32 s56, s56, 1
	s_or_b32 s56, s56, s57
	s_lshl_b32 s56, s56, 2
	s_load_dwordx2 s[28:29], s[50:51], s56
	v_ashrrev_i32_e32 v230, 6, v0
	v_lshlrev_b32_e32 v231, 2, v0
	v_and_b32_e32 v231, 0xfc, v231
	v_lshlrev_b32_e32 v231, 2, v231
	v_lshl_add_u32 v230, v230, 12, v231
	s_waitcnt lgkmcnt(0)
	s_bitcmp1_b32 s99, 5
	s_cselect_b32 s28, s29, s28
	s_lshl_b32 s28, s28, 19
	v_add_u32_e32 v231, s28, v230
	s_and_b32 s56, s99, 63
	s_cmp_lg_u32 s56, 0
	s_cbranch_scc1 .Lks_done
	v_mov_b32_e32 v222, 0
	v_mov_b32_e32 v223, 0
	v_mov_b32_e32 v224, 0
	v_mov_b32_e32 v225, 0
	v_mov_b32_e32 v226, 0
	v_mov_b32_e32 v227, 0
	v_mov_b32_e32 v228, 0
	v_mov_b32_e32 v229, 0

;     static DI int kmap(int kt) { return (kt >> 1) + 16 * (kt & 1); }
; DI void kmean_item(const float* __restrict__ base, const int* __restrict__ pt, int b, int n, float* __restrict__ outp, char* sm) {
;     ...
; #pragma unroll 4
;         for (int rr = 0; rr < 32; ++rr) {
;             a0 += __builtin_nontemporal_load((const f32x4*)(rp + (size_t)rr * 4096));
;             a1 += __builtin_nontemporal_load((const f32x4*)(rp + (size_t)rr * 4096 + 256));
;         }
; template <class AL>
; DI void gemm_mainloop(f32x16 (&acc)[2][2], GemmRegs<AL>& G, bool pre, const AL& al, const u16* __restrict__ Bt, int ldb, int n0, int nk, char* sm,
;                       bool has_next, const AL& aln, int n0n) {
;     ...
;     for (int kt = 0; kt < nk; kt += 2) {
;         compute(buf0);
;         store(RA1, RB1, kt + 1, buf1);
;         if (kt + 3 < nk) { al.load(RA1, AL::kmap(kt + 3)); loadB(RB1, AL::kmap(kt + 3)); }
;         else if (has_next) { aln.load(RA1, AL::kmap(1)); loadBn(RB1, AL::kmap(1)); }
;         __syncthreads();
;         compute(buf1);
;         if (kt + 2 < nk) {
;             store(RA0, RB0, kt + 2, buf0);
;             if (kt + 4 < nk) { al.load(RA0, AL::kmap(kt + 4)); loadB(RB0, AL::kmap(kt + 4)); }
;             else if (has_next) { aln.load(RA0, AL::kmap(0)); loadBn(RB0, AL::kmap(0)); }
;         }
;         __syncthreads();
;     }
.Lg1_loop:
	s_setprio 1
	v_add_u32_e32 v174, v168, v169
	v_add_u32_e32 v175, v170, v169
	v_add_u32_e32 v176, v168, v171
	v_add_u32_e32 v177, v170, v171
	ds_read_b128 v[150:153], v174
	ds_read_b128 v[154:157], v174 offset:4096
	ds_read_b128 v[158:161], v175 offset:16384
	ds_read_b128 v[162:165], v175 offset:20480
	ds_read_b128 v[180:183], v176
	ds_read_b128 v[184:187], v176 offset:4096
	ds_read_b128 v[188:191], v177 offset:16384
	ds_read_b128 v[192:195], v177 offset:20480
	s_mov_b32 m0, s58
	s_nop 0
	global_load_lds_dwordx4 v136, s[2:3]
	global_load_lds_dwordx4 v137, s[2:3] offset:1024
	global_load_lds_dwordx4 v138, s[2:3] offset:2048
	global_load_lds_dwordx4 v139, s[2:3] offset:3072
	s_add_u32 s2, s2, 0x80
	s_addc_u32 s3, s3, 0
	s_waitcnt lgkmcnt(5)
	v_mfma_f32_32x32x16_bf16 v[50:65], v[150:153], v[158:161], v[50:65]
	v_add_u32_e32 v178, v168, v172
	v_add_u32_e32 v179, v170, v172
	s_waitcnt lgkmcnt(4)
	v_mfma_f32_32x32x16_bf16 v[34:49], v[150:153], v[162:165], v[34:49]
	v_mfma_f32_32x32x16_bf16 v[18:33], v[154:157], v[158:161], v[18:33]
	v_mfma_f32_32x32x16_bf16 v[2:17], v[154:157], v[162:165], v[2:17]
	s_cmp_lt_u32 s43, 2
	s_cbranch_scc1 .Lkce
	s_cmp_lt_u32 s100, 1
	s_cbranch_scc1 .Lkce
	v_pk_add_f32 v[222:223], v[222:223], v[66:67]
	v_pk_add_f32 v[224:225], v[224:225], v[68:69]
	v_pk_add_f32 v[226:227], v[226:227], v[70:71]
	v_pk_add_f32 v[228:229], v[228:229], v[72:73]
	s_cmp_lt_u32 s100, 2
	s_cbranch_scc1 .Lkce
	v_pk_add_f32 v[222:223], v[222:223], v[74:75]
	v_pk_add_f32 v[224:225], v[224:225], v[76:77]
	v_pk_add_f32 v[226:227], v[226:227], v[78:79]
	v_pk_add_f32 v[228:229], v[228:229], v[80:81]
.Lkce:
	ds_read_b128 v[150:153], v178
	ds_read_b128 v[154:157], v178 offset:4096
	ds_read_b128 v[158:161], v179 offset:16384
	ds_read_b128 v[162:165], v179 offset:20480
	s_mov_b32 m0, s59
	s_nop 0
	global_load_lds_dwordx4 v136, s[64:65]
	global_load_lds_dwordx4 v137, s[64:65] offset:1024
	global_load_lds_dwordx4 v138, s[64:65] offset:2048
	global_load_lds_dwordx4 v139, s[64:65] offset:3072
	s_add_u32 s64, s64, 0x80
	s_addc_u32 s65, s65, 0
	s_cmp_lt_u32 s100, 1
	s_cbranch_scc1 .Lkie
	s_and_b32 s22, s99, 0x1c
	s_lshl_b32 s22, s22, 14
	s_and_b32 s23, s99, 3
	s_lshl_b32 s23, s23, 14
	s_add_i32 s22, s22, s23
	s_add_u32 s66, s44, s22
	s_addc_u32 s67, s45, 0
	global_load_dwordx4 v[66:69], v231, s[66:67] nt
	global_load_dwordx4 v[70:73], v231, s[66:67] offset:1024 nt
	s_add_i32 s99, s99, 1
	s_cmp_lt_u32 s100, 2
	s_cbranch_scc1 .Lkie
	s_and_b32 s22, s99, 0x1c
	s_lshl_b32 s22, s22, 14
	s_and_b32 s23, s99, 3
	s_lshl_b32 s23, s23, 14
	s_add_i32 s22, s22, s23
	s_add_u32 s66, s44, s22
	s_addc_u32 s67, s45, 0
	global_load_dwordx4 v[74:77], v231, s[66:67] nt
	global_load_dwordx4 v[78:81], v231, s[66:67] offset:1024 nt
	s_add_i32 s99, s99, 1
.Lkie:
	s_waitcnt lgkmcnt(5)
	v_mfma_f32_32x32x16_bf16 v[50:65], v[180:183], v[188:191], v[50:65]
	s_waitcnt lgkmcnt(4)
	v_mfma_f32_32x32x16_bf16 v[34:49], v[180:183], v[192:195], v[34:49]
	v_add_u32_e32 v180, v168, v173
	v_add_u32_e32 v181, v170, v173
	v_mfma_f32_32x32x16_bf16 v[18:33], v[184:187], v[188:191], v[18:33]
	v_mfma_f32_32x32x16_bf16 v[2:17], v[184:187], v[192:195], v[2:17]
	ds_read_b128 v[182:185], v180
	ds_read_b128 v[186:189], v180 offset:4096
	ds_read_b128 v[190:193], v181 offset:16384
	ds_read_b128 v[194:197], v181 offset:20480
	s_waitcnt lgkmcnt(5)
	v_mfma_f32_32x32x16_bf16 v[50:65], v[150:153], v[158:161], v[50:65]
	s_waitcnt lgkmcnt(4)
	v_mfma_f32_32x32x16_bf16 v[34:49], v[150:153], v[162:165], v[34:49]
	v_mfma_f32_32x32x16_bf16 v[18:33], v[154:157], v[158:161], v[18:33]
	v_mfma_f32_32x32x16_bf16 v[2:17], v[154:157], v[162:165], v[2:17]
	s_waitcnt lgkmcnt(1)
	v_mfma_f32_32x32x16_bf16 v[50:65], v[182:185], v[190:193], v[50:65]
	s_waitcnt lgkmcnt(0)
	v_mfma_f32_32x32x16_bf16 v[34:49], v[182:185], v[194:197], v[34:49]
	v_mfma_f32_32x32x16_bf16 v[18:33], v[186:189], v[190:193], v[18:33]
	v_mfma_f32_32x32x16_bf16 v[2:17], v[186:189], v[194:197], v[2:17]
	s_cmp_lt_u32 s100, 1
	s_cbranch_scc1 .Lkwe0
	s_cmp_lt_u32 s100, 2
	s_cbranch_scc1 .Lkwe1
	s_waitcnt vmcnt(4)
	s_branch .Lkweb
.Lkwe1:
	s_waitcnt vmcnt(2)
	s_branch .Lkweb

;     static DI int kmap(int kt) { return (kt >> 1) + 16 * (kt & 1); }
; template <class AL>
; DI void gemm_mainloop(f32x16 (&acc)[2][2], GemmRegs<AL>& G, bool pre, const AL& al, const u16* __restrict__ Bt, int ldb, int n0, int nk, char* sm,
;                       bool has_next, const AL& aln, int n0n) {
;     ...
;         if (kt + 3 < nk) { al.load(RA1, AL::kmap(kt + 3)); loadB(RB1, AL::kmap(kt + 3)); }
;         else if (has_next) { aln.load(RA1, AL::kmap(1)); loadBn(RB1, AL::kmap(1)); }
;         __syncthreads();
.Lkweb:
	s_barrier
	s_mov_b32 s53, 1
	s_cmp_lt_u32 s43, 14
	s_cbranch_scc1 .Lg1_bgo
	s_mov_b32 s53, 0
	s_and_b64 vcc, exec, s[0:1]
	s_cbranch_vccz .Lg1_bgo
	s_mov_b32 s53, 1
	s_lshl_b32 s26, s94, 18
	s_add_u32 s2, s6, s26
	s_addc_u32 s3, s7, 0
	s_lshl_b32 s26, s93, 18
	s_add_u32 s64, s8, s26
	s_addc_u32 s65, s9, 0

;     static DI int kmap(int kt) { return (kt >> 1) + 16 * (kt & 1); }
; DI void kmean_item(const float* __restrict__ base, const int* __restrict__ pt, int b, int n, float* __restrict__ outp, char* sm) {
;     ...
; #pragma unroll 4
;         for (int rr = 0; rr < 32; ++rr) {
;             a0 += __builtin_nontemporal_load((const f32x4*)(rp + (size_t)rr * 4096));
;             a1 += __builtin_nontemporal_load((const f32x4*)(rp + (size_t)rr * 4096 + 256));
;         }
; template <class AL>
; DI void gemm_mainloop(f32x16 (&acc)[2][2], GemmRegs<AL>& G, bool pre, const AL& al, const u16* __restrict__ Bt, int ldb, int n0, int nk, char* sm,
;                       bool has_next, const AL& aln, int n0n) {
;     ...
;     for (int kt = 0; kt < nk; kt += 2) {
;         compute(buf0);
;         store(RA1, RB1, kt + 1, buf1);
;         if (kt + 3 < nk) { al.load(RA1, AL::kmap(kt + 3)); loadB(RB1, AL::kmap(kt + 3)); }
;         else if (has_next) { aln.load(RA1, AL::kmap(1)); loadBn(RB1, AL::kmap(1)); }
;         __syncthreads();
;         compute(buf1);
;         if (kt + 2 < nk) {
;             store(RA0, RB0, kt + 2, buf0);
;             if (kt + 4 < nk) { al.load(RA0, AL::kmap(kt + 4)); loadB(RB0, AL::kmap(kt + 4)); }
;             else if (has_next) { aln.load(RA0, AL::kmap(0)); loadBn(RB0, AL::kmap(0)); }
;         }
;         __syncthreads();
;     }
.Lg1_skipA:
	s_waitcnt lgkmcnt(5)
	v_mfma_f32_32x32x16_bf16 v[50:65], v[150:153], v[158:161], v[50:65]
	s_waitcnt lgkmcnt(4)
	v_mfma_f32_32x32x16_bf16 v[34:49], v[150:153], v[162:165], v[34:49]
	v_mfma_f32_32x32x16_bf16 v[18:33], v[154:157], v[158:161], v[18:33]
	v_mfma_f32_32x32x16_bf16 v[2:17], v[154:157], v[162:165], v[2:17]
	s_cmp_lt_u32 s43, 2
	s_cbranch_scc1 .Lkco
	s_cmp_lt_u32 s100, 1
	s_cbranch_scc1 .Lkco
	v_pk_add_f32 v[222:223], v[222:223], v[82:83]
	v_pk_add_f32 v[224:225], v[224:225], v[84:85]
	v_pk_add_f32 v[226:227], v[226:227], v[86:87]
	v_pk_add_f32 v[228:229], v[228:229], v[88:89]
	s_cmp_lt_u32 s100, 2
	s_cbranch_scc1 .Lkco
	v_pk_add_f32 v[222:223], v[222:223], v[90:91]
	v_pk_add_f32 v[224:225], v[224:225], v[92:93]
	v_pk_add_f32 v[226:227], v[226:227], v[94:95]
	v_pk_add_f32 v[228:229], v[228:229], v[96:97]
.Lkco:
	ds_read_b128 v[150:153], v178 offset:32768
	ds_read_b128 v[154:157], v178 offset:36864
	ds_read_b128 v[158:161], v179 offset:49152
	ds_read_b128 v[162:165], v179 offset:53248
	s_cmp_eq_u32 s53, 0
	s_cbranch_scc1 .Lg1_skipB
	s_mov_b32 m0, s57
	s_nop 0
	global_load_lds_dwordx4 v136, s[64:65]
	global_load_lds_dwordx4 v137, s[64:65] offset:1024
	global_load_lds_dwordx4 v138, s[64:65] offset:2048
	global_load_lds_dwordx4 v139, s[64:65] offset:3072
	s_add_u32 s64, s64, 0x80
	s_addc_u32 s65, s65, 0
.Lg1_skipB:
	s_cmp_lt_u32 s100, 1
	s_cbranch_scc1 .Lkio
	s_and_b32 s22, s99, 0x1c
	s_lshl_b32 s22, s22, 14
	s_and_b32 s23, s99, 3
	s_lshl_b32 s23, s23, 14
	s_add_i32 s22, s22, s23
	s_add_u32 s66, s44, s22
	s_addc_u32 s67, s45, 0
	global_load_dwordx4 v[82:85], v231, s[66:67] nt
	global_load_dwordx4 v[86:89], v231, s[66:67] offset:1024 nt
	s_add_i32 s99, s99, 1
	s_cmp_lt_u32 s100, 2
	s_cbranch_scc1 .Lkio
	s_and_b32 s22, s99, 0x1c
	s_lshl_b32 s22, s22, 14
	s_and_b32 s23, s99, 3
	s_lshl_b32 s23, s23, 14
	s_add_i32 s22, s22, s23
	s_add_u32 s66, s44, s22
	s_addc_u32 s67, s45, 0
	global_load_dwordx4 v[90:93], v231, s[66:67] nt
	global_load_dwordx4 v[94:97], v231, s[66:67] offset:1024 nt
	s_add_i32 s99, s99, 1
.Lkio:
	s_waitcnt lgkmcnt(5)
	v_mfma_f32_32x32x16_bf16 v[50:65], v[182:185], v[190:193], v[50:65]
	s_waitcnt lgkmcnt(4)
	v_mfma_f32_32x32x16_bf16 v[34:49], v[182:185], v[174:177], v[34:49]
	v_mfma_f32_32x32x16_bf16 v[18:33], v[186:189], v[190:193], v[18:33]
	v_mfma_f32_32x32x16_bf16 v[2:17], v[186:189], v[174:177], v[2:17]
	ds_read_b128 v[174:177], v180 offset:32768
	ds_read_b128 v[182:185], v180 offset:36864
	ds_read_b128 v[186:189], v181 offset:49152
	ds_read_b128 v[178:181], v181 offset:53248
	s_waitcnt lgkmcnt(5)
	v_mfma_f32_32x32x16_bf16 v[50:65], v[150:153], v[158:161], v[50:65]
	s_waitcnt lgkmcnt(4)
	v_mfma_f32_32x32x16_bf16 v[34:49], v[150:153], v[162:165], v[34:49]
	v_mfma_f32_32x32x16_bf16 v[18:33], v[154:157], v[158:161], v[18:33]
	v_mfma_f32_32x32x16_bf16 v[2:17], v[154:157], v[162:165], v[2:17]
	s_waitcnt lgkmcnt(1)
	v_mfma_f32_32x32x16_bf16 v[50:65], v[174:177], v[186:189], v[50:65]
	s_waitcnt lgkmcnt(0)
	v_mfma_f32_32x32x16_bf16 v[34:49], v[174:177], v[178:181], v[34:49]
	v_mfma_f32_32x32x16_bf16 v[18:33], v[182:185], v[186:189], v[18:33]
	v_mfma_f32_32x32x16_bf16 v[2:17], v[182:185], v[178:181], v[2:17]
	s_cmp_lt_u32 s100, 1
	s_cbranch_scc1 .Lkwo0
	s_cmp_lt_u32 s100, 2
	s_cbranch_scc1 .Lkwo1
	s_waitcnt vmcnt(4)
	s_branch .Lkwob

; DI int opaque(int v) { asm volatile("" : "+v"(v)); return v; }
; DI void kmean_item(const float* __restrict__ base, const int* __restrict__ pt, int b, int n, float* __restrict__ outp, char* sm) {
;     ...
;     *(f32x4*)(scr + w * 512 + lane * 4) = a0;
;     *(f32x4*)(scr + w * 512 + 256 + lane * 4) = a1;
;     __syncthreads();
; #pragma unroll
;     for (int j = 0; j < 2; ++j) {
;         const int col = t + 256 * j;
;         outp[col] = (scr[col] + scr[512 + col] + scr[1024 + col] + scr[1536 + col]) * (1.f / 256.f);
;     }
;     __syncthreads();
; DI void gemm1_tile(const Params& p, GemmRegs<ALoadBf16>& G, bool pre, int tm, int tn, bool has_next, int tmn, int tnn, char* sm) {
;     ...
;     const int t_ = opaque(threadIdx.x), lane = t_ & 63, w = t_ >> 6, wm = w >> 1, wn = w & 1, r = lane & 31, h = lane >> 5;
;     const bool smp = tm == 128;
;     const size_t rloc = (size_t)(smp ? 0 : tm * 128) + wm * 64 + 4 * h;
;     const size_t rall = (size_t)tm * 128 + wm * 64 + 4 * h;
;     const int cl = wn * 64 + r;
;     if (tn < 4) epi_store<512, 1>(acc, nullptr, (u16*)(p.ws + WS_QM) + rall * 512 + tn * 128 + cl);
;     else if (tn < 12) {
;         epi_store<1024, 0>(acc, p.out + (smp ? O_MKS : O_MKP) + rloc * 1024 + (tn - 4) * 128 + cl, nullptr);
;         if (!smp) {
;             u16* dst = (u16*)(p.ws + (tn < 8 ? WS_KMB : WS_VMB)) + (((size_t)(tm >> 6) * 8 + 2 * (tn & 3) + wn) * 8192 + (tm & 63) * 128 + wm * 64 + 4 * h) * 64 + r;
;             epi_store<64, 1>(acc, nullptr, dst);
;             if (tn < 8) {
;                 float* kp = (float*)(p.ws + WS_KMP) + ((((size_t)(tm >> 6) * 32 + ((tm & 63) >> 1)) * 4 + (tm & 1) * 2 + wm) * 512) + (tn - 4) * 128 + cl;
; #pragma unroll
;                 for (int ni = 0; ni < 2; ++ni) {
;                     float cs = 0.f;
; #pragma unroll
;                     for (int mi = 0; mi < 2; ++mi)
; #pragma unroll
;                         for (int i = 0; i < 16; ++i) cs += acc[mi][ni][i];
;                     cs += __shfl_xor(cs, 32);
;                     if (h == 0) kp[ni * 32] = cs;
;                 }
;             }
;         }
;     }
;     else if (tn < 16) epi_store<512, 2>(acc, nullptr, (u16*)(p.ws + WS_ZM) + rall * 512 + (tn - 12) * 128 + cl);
;     else if (tn < 20) epi_store<512, 1>(acc, nullptr, (u16*)(p.ws + WS_QN) + rall * 512 + (tn - 16) * 128 + cl);
;     else if (tn < 24) {
.Lkwob:
	s_barrier
	s_add_i32 s43, s43, 2
	s_cmp_lt_u32 s43, 16
	s_cbranch_scc1 .Lg1_loop
	s_setprio 0
	s_cmp_lt_u32 s100, 1
	s_cbranch_scc1 .Lkf_done
	s_waitcnt vmcnt(0)
	s_cmp_lt_u32 s100, 1
	s_cbranch_scc1 .Lkcfe
	v_pk_add_f32 v[222:223], v[222:223], v[66:67]
	v_pk_add_f32 v[224:225], v[224:225], v[68:69]
	v_pk_add_f32 v[226:227], v[226:227], v[70:71]
	v_pk_add_f32 v[228:229], v[228:229], v[72:73]
	s_cmp_lt_u32 s100, 2
	s_cbranch_scc1 .Lkcfe
	v_pk_add_f32 v[222:223], v[222:223], v[74:75]
	v_pk_add_f32 v[224:225], v[224:225], v[76:77]
	v_pk_add_f32 v[226:227], v[226:227], v[78:79]
	v_pk_add_f32 v[228:229], v[228:229], v[80:81]
.Lkcfe:
	s_cmp_lt_u32 s100, 1
	s_cbranch_scc1 .Lkcfo
	v_pk_add_f32 v[222:223], v[222:223], v[82:83]
	v_pk_add_f32 v[224:225], v[224:225], v[84:85]
	v_pk_add_f32 v[226:227], v[226:227], v[86:87]
	v_pk_add_f32 v[228:229], v[228:229], v[88:89]
	s_cmp_lt_u32 s100, 2
	s_cbranch_scc1 .Lkcfo
	v_pk_add_f32 v[222:223], v[222:223], v[90:91]
	v_pk_add_f32 v[224:225], v[224:225], v[92:93]
	v_pk_add_f32 v[226:227], v[226:227], v[94:95]
	v_pk_add_f32 v[228:229], v[228:229], v[96:97]
.Lkcfo:
	s_and_b32 s22, s99, 63
	s_cmp_lg_u32 s22, 0
	s_cbranch_scc1 .Lkf_done
	v_ashrrev_i32_e32 v210, 6, v0
	v_lshlrev_b32_e32 v211, 2, v0
	v_and_b32_e32 v211, 0xfc, v211
	v_lshlrev_b32_e32 v211, 2, v211
	v_lshlrev_b32_e32 v209, 11, v210
	v_add_u32_e32 v209, v209, v211
	v_add_u32_e32 v209, 0x8000, v209
	ds_write_b128 v209, v[222:225]
	ds_write_b128 v209, v[226:229] offset:1024
	v_lshlrev_b32_e32 v212, 2, v0
	v_add_u32_e32 v213, 0x8000, v212
	s_lshl_b32 s22, s101, 11
	s_add_u32 s66, s62, s22
	s_addc_u32 s67, s63, 0
	s_add_u32 s66, s66, 0xbb6000
	s_addc_u32 s67, s67, 0
	s_waitcnt lgkmcnt(0)
	s_barrier
	ds_read2st64_b32 v[214:215], v213 offset1:4
	ds_read2st64_b32 v[216:217], v213 offset0:8 offset1:12
	ds_read2st64_b32 v[218:219], v213 offset0:16 offset1:20
	ds_read2st64_b32 v[220:221], v213 offset0:24 offset1:28
	s_waitcnt lgkmcnt(2)
	v_add_f32_e32 v209, v214, v216
	s_waitcnt lgkmcnt(1)
	v_add_f32_e32 v209, v209, v218
	s_waitcnt lgkmcnt(0)
	v_add_f32_e32 v209, v209, v220
	v_mul_f32_e32 v209, 0x3b800000, v209
	global_store_dword v212, v209, s[66:67]
	v_add_f32_e32 v209, v215, v217
	v_add_f32_e32 v209, v209, v219
	v_add_f32_e32 v209, v209, v221
	v_mul_f32_e32 v209, 0x3b800000, v209
	global_store_dword v212, v209, s[66:67] offset:1024
	s_barrier
.Lkf_done:
.LBB0_289:
	v_mov_b32_e32 v130, v0
	s_mov_b32 s43, s27
	v_ashrrev_i32_e32 v132, 7, v130
	v_lshlrev_b32_e32 v136, 6, v132
	v_bfe_u32 v151, v130, 5, 1
	v_ashrrev_i32_e32 v137, 31, v136
	s_lshl_b64 s[0:1], s[42:43], 7
	v_bfe_u32 v152, v130, 6, 1
	v_and_b32_e32 v133, 31, v130
	v_lshlrev_b32_e32 v153, 2, v151
	v_lshl_add_u64 v[130:131], s[0:1], 0, v[136:137]
	v_or_b32_e32 v130, v130, v153
	v_lshl_or_b32 v150, v152, 6, v133
	s_cmp_gt_i32 s95, 3
	s_mov_b64 s[0:1], -1
	s_cbranch_scc0 .LBB0_328
	s_cmpk_eq_i32 s42, 0x80
	s_cselect_b64 s[64:65], -1, 0
	s_cmpk_lg_i32 s42, 0x80
	s_cselect_b64 s[56:57], -1, 0
	s_and_b64 s[0:1], s[56:57], exec
	s_cselect_b32 s0, s16, 0
	s_ashr_i32 s1, s0, 31
	v_lshl_add_u64 v[138:139], v[136:137], 0, s[0:1]
	v_or_b32_e32 v138, v138, v153
	s_cmp_gt_u32 s95, 11
	s_mov_b64 s[0:1], -1
	s_cbranch_scc0 .LBB0_319
	s_cmp_gt_u32 s95, 15
	s_cbranch_scc0 .LBB0_316
	s_cmp_gt_u32 s95, 19
	s_cbranch_scc0 .LBB0_313
	s_cmp_gt_u32 s95, 23
	s_cbranch_scc0 .LBB0_309
	s_cmp_gt_u32 s95, 25
	s_cbranch_scc0 .LBB0_302
	s_cmp_gt_u32 s95, 29
	s_cbranch_scc0 .LBB0_299
	v_cmp_eq_u32_e32 vcc, 0, v152
	v_cmp_gt_u32_e64 s[0:1], 24, v133
	s_and_b64 s[2:3], vcc, s[0:1]
	s_and_saveexec_b64 s[0:1], s[2:3]
	s_cbranch_execz .LBB0_298
	v_mul_f32_e32 v134, 0xbfb8aa3b, v50
	v_mov_b64_e32 v[140:141], s[10:11]
	s_movk_i32 s17, 0x60
	v_exp_f32_e32 v144, v134
	v_mad_u64_u32 v[140:141], s[2:3], v130, s17, v[140:141]
	v_mov_b32_e32 v134, v141
	v_mad_u64_u32 v[142:143], s[2:3], v131, s17, v[134:135]
	v_add_f32_e32 v143, 1.0, v144
	v_div_scale_f32 v144, s[2:3], v143, v143, 1.0
	v_rcp_f32_e32 v145, v144
	v_mov_b32_e32 v141, v142
	v_lshlrev_b32_e32 v134, 2, v133
	v_lshl_add_u64 v[140:141], v[140:141], 0, v[134:135]
	v_fma_f32 v134, -v144, v145, 1.0
	v_mul_f32_e32 v146, 0xbfb8aa3b, v51
	v_fmac_f32_e32 v145, v134, v145
	v_div_scale_f32 v134, vcc, 1.0, v143, 1.0
	v_exp_f32_e32 v146, v146
	v_mul_f32_e32 v142, v134, v145
	v_fma_f32 v147, -v144, v142, v134
	v_fmac_f32_e32 v142, v147, v145
	v_fma_f32 v134, -v144, v142, v134
	v_add_f32_e32 v144, 1.0, v146
	v_div_scale_f32 v146, s[2:3], v144, v144, 1.0
	v_rcp_f32_e32 v147, v146
	v_div_fmas_f32 v134, v134, v145, v142
	v_div_fixup_f32 v134, v134, v143, 1.0
	v_mul_f32_e32 v143, 0xbfb8aa3b, v52
	v_exp_f32_e32 v143, v143
	global_store_dword v[140:141], v134, off
	v_fma_f32 v134, -v146, v147, 1.0
	v_fmac_f32_e32 v147, v134, v147
	v_div_scale_f32 v134, vcc, 1.0, v144, 1.0
	v_mul_f32_e32 v142, v134, v147
	v_fma_f32 v145, -v146, v142, v134
	v_add_f32_e32 v143, 1.0, v143
	v_fmac_f32_e32 v142, v145, v147
	v_div_scale_f32 v145, s[2:3], v143, v143, 1.0
	v_fma_f32 v134, -v146, v142, v134
	v_rcp_f32_e32 v146, v145
	v_div_fmas_f32 v134, v134, v147, v142
	v_div_fixup_f32 v134, v134, v144, 1.0
	v_mul_f32_e32 v144, 0xbfb8aa3b, v53
	global_store_dword v[140:141], v134, off offset:96
	v_fma_f32 v134, -v145, v146, 1.0
	v_exp_f32_e32 v144, v144
	v_fmac_f32_e32 v146, v134, v146
	v_div_scale_f32 v134, vcc, 1.0, v143, 1.0
	v_mul_f32_e32 v142, v134, v146
	v_fma_f32 v147, -v145, v142, v134
	v_fmac_f32_e32 v142, v147, v146
	v_add_f32_e32 v144, 1.0, v144
	v_fma_f32 v134, -v145, v142, v134
	v_div_scale_f32 v145, s[2:3], v144, v144, 1.0
	v_rcp_f32_e32 v147, v145
	v_div_fmas_f32 v134, v134, v146, v142
; DI float sigmoid_f(float z) { return 1.f / (1.f + __expf(-z)); }
; DI void gemm1_tile(const Params& p, GemmRegs<ALoadBf16>& G, bool pre, int tm, int tn, bool has_next, int tmn, int tnn, char* sm) {
;     ...
;         if (wn == 0 && r < 24) {
;             float* gb = (float*)(p.ws + WS_GATES) + rall * 24 + r;
; #pragma unroll
;             for (int mi = 0; mi < 2; ++mi)
; #pragma unroll
;                 for (int i = 0; i < 16; ++i) gb[(mi * 32 + (i & 3) + 8 * (i >> 2)) * 24] = sigmoid_f(acc[mi][0][i]);
;         }
	v_div_fixup_f32 v134, v134, v143, 1.0
	v_mul_f32_e32 v143, 0xbfb8aa3b, v54
	global_store_dword v[140:141], v134, off offset:192
	v_fma_f32 v134, -v145, v147, 1.0
	v_exp_f32_e32 v143, v143
	v_fmac_f32_e32 v147, v134, v147
	v_div_scale_f32 v134, vcc, 1.0, v144, 1.0
	v_mul_f32_e32 v142, v134, v147
	v_fma_f32 v146, -v145, v142, v134
	v_fmac_f32_e32 v142, v146, v147
	v_add_f32_e32 v143, 1.0, v143
	v_fma_f32 v134, -v145, v142, v134
	v_div_scale_f32 v145, s[2:3], v143, v143, 1.0
	v_rcp_f32_e32 v146, v145
	v_div_fmas_f32 v134, v134, v147, v142
	v_div_fixup_f32 v134, v134, v144, 1.0
	v_mul_f32_e32 v144, 0xbfb8aa3b, v55
	global_store_dword v[140:141], v134, off offset:288
	v_fma_f32 v134, -v145, v146, 1.0
	v_exp_f32_e32 v144, v144
	v_fmac_f32_e32 v146, v134, v146
	v_div_scale_f32 v134, vcc, 1.0, v143, 1.0
	v_mul_f32_e32 v142, v134, v146
	v_fma_f32 v147, -v145, v142, v134
	v_fmac_f32_e32 v142, v147, v146
	v_add_f32_e32 v144, 1.0, v144
	v_fma_f32 v134, -v145, v142, v134
	v_div_scale_f32 v145, s[2:3], v144, v144, 1.0
	v_rcp_f32_e32 v147, v145
	v_div_fmas_f32 v134, v134, v146, v142
	v_div_fixup_f32 v134, v134, v143, 1.0
	v_mul_f32_e32 v143, 0xbfb8aa3b, v56
	global_store_dword v[140:141], v134, off offset:768
	v_fma_f32 v134, -v145, v147, 1.0
	v_exp_f32_e32 v143, v143
	v_fmac_f32_e32 v147, v134, v147
	v_div_scale_f32 v134, vcc, 1.0, v144, 1.0
	v_mul_f32_e32 v142, v134, v147
	v_fma_f32 v146, -v145, v142, v134
	v_fmac_f32_e32 v142, v146, v147
	v_add_f32_e32 v143, 1.0, v143
	v_fma_f32 v134, -v145, v142, v134
	v_div_scale_f32 v145, s[2:3], v143, v143, 1.0
	v_rcp_f32_e32 v146, v145
	v_div_fmas_f32 v134, v134, v147, v142
	v_div_fixup_f32 v134, v134, v144, 1.0
	v_mul_f32_e32 v144, 0xbfb8aa3b, v57
	global_store_dword v[140:141], v134, off offset:864
	v_fma_f32 v134, -v145, v146, 1.0
	v_exp_f32_e32 v144, v144
	v_fmac_f32_e32 v146, v134, v146
	v_div_scale_f32 v134, vcc, 1.0, v143, 1.0
	v_mul_f32_e32 v142, v134, v146
	v_fma_f32 v147, -v145, v142, v134
	v_fmac_f32_e32 v142, v147, v146
	v_add_f32_e32 v144, 1.0, v144
	v_fma_f32 v134, -v145, v142, v134
	v_div_scale_f32 v145, s[2:3], v144, v144, 1.0
	v_rcp_f32_e32 v147, v145
	v_div_fmas_f32 v134, v134, v146, v142
	v_div_fixup_f32 v134, v134, v143, 1.0
	v_mul_f32_e32 v143, 0xbfb8aa3b, v58
	global_store_dword v[140:141], v134, off offset:960
	v_fma_f32 v134, -v145, v147, 1.0
	v_exp_f32_e32 v143, v143
	v_fmac_f32_e32 v147, v134, v147
	v_div_scale_f32 v134, vcc, 1.0, v144, 1.0
	v_mul_f32_e32 v142, v134, v147
	v_fma_f32 v146, -v145, v142, v134
	v_fmac_f32_e32 v142, v146, v147
	v_add_f32_e32 v143, 1.0, v143
	v_fma_f32 v134, -v145, v142, v134
	v_div_scale_f32 v145, s[2:3], v143, v143, 1.0
	v_rcp_f32_e32 v146, v145
	v_div_fmas_f32 v134, v134, v147, v142
	v_div_fixup_f32 v134, v134, v144, 1.0
	v_mul_f32_e32 v144, 0xbfb8aa3b, v59
	global_store_dword v[140:141], v134, off offset:1056
	v_fma_f32 v134, -v145, v146, 1.0
	v_exp_f32_e32 v144, v144
	v_fmac_f32_e32 v146, v134, v146
	v_div_scale_f32 v134, vcc, 1.0, v143, 1.0
	v_mul_f32_e32 v142, v134, v146
	v_fma_f32 v147, -v145, v142, v134
	v_fmac_f32_e32 v142, v147, v146
	v_add_f32_e32 v144, 1.0, v144
	v_fma_f32 v134, -v145, v142, v134
	v_div_scale_f32 v145, s[2:3], v144, v144, 1.0
	v_rcp_f32_e32 v147, v145
	v_div_fmas_f32 v134, v134, v146, v142
	v_div_fixup_f32 v134, v134, v143, 1.0
	v_mul_f32_e32 v143, 0xbfb8aa3b, v60
	global_store_dword v[140:141], v134, off offset:1536
	v_fma_f32 v134, -v145, v147, 1.0
	v_exp_f32_e32 v143, v143
	v_fmac_f32_e32 v147, v134, v147
	v_div_scale_f32 v134, vcc, 1.0, v144, 1.0
	v_mul_f32_e32 v142, v134, v147
	v_fma_f32 v146, -v145, v142, v134
	v_fmac_f32_e32 v142, v146, v147
	v_add_f32_e32 v143, 1.0, v143
	v_fma_f32 v134, -v145, v142, v134
	v_div_scale_f32 v145, s[2:3], v143, v143, 1.0
	v_rcp_f32_e32 v146, v145
	v_div_fmas_f32 v134, v134, v147, v142
	v_div_fixup_f32 v134, v134, v144, 1.0
	v_mul_f32_e32 v144, 0xbfb8aa3b, v61
	global_store_dword v[140:141], v134, off offset:1632
	v_fma_f32 v134, -v145, v146, 1.0
	v_exp_f32_e32 v144, v144
	v_fmac_f32_e32 v146, v134, v146
	v_div_scale_f32 v134, vcc, 1.0, v143, 1.0
	v_mul_f32_e32 v142, v134, v146
	v_fma_f32 v147, -v145, v142, v134
	v_fmac_f32_e32 v142, v147, v146
	v_add_f32_e32 v144, 1.0, v144
	v_fma_f32 v134, -v145, v142, v134
	v_div_scale_f32 v145, s[2:3], v144, v144, 1.0
	v_rcp_f32_e32 v147, v145
	v_div_fmas_f32 v134, v134, v146, v142
	v_div_fixup_f32 v134, v134, v143, 1.0
	v_mul_f32_e32 v143, 0xbfb8aa3b, v62
	global_store_dword v[140:141], v134, off offset:1728
	v_fma_f32 v134, -v145, v147, 1.0
	v_exp_f32_e32 v143, v143
	v_fmac_f32_e32 v147, v134, v147
	v_div_scale_f32 v134, vcc, 1.0, v144, 1.0
	v_mul_f32_e32 v142, v134, v147
	v_fma_f32 v146, -v145, v142, v134
	v_fmac_f32_e32 v142, v146, v147
	v_add_f32_e32 v143, 1.0, v143
	v_fma_f32 v134, -v145, v142, v134
	v_div_scale_f32 v145, s[2:3], v143, v143, 1.0
	v_rcp_f32_e32 v146, v145
	v_div_fmas_f32 v134, v134, v147, v142
	v_div_fixup_f32 v134, v134, v144, 1.0
	v_mul_f32_e32 v144, 0xbfb8aa3b, v63
	global_store_dword v[140:141], v134, off offset:1824
	v_fma_f32 v134, -v145, v146, 1.0
	v_exp_f32_e32 v144, v144
	v_fmac_f32_e32 v146, v134, v146
	v_div_scale_f32 v134, vcc, 1.0, v143, 1.0
	v_mul_f32_e32 v142, v134, v146
	v_fma_f32 v147, -v145, v142, v134
	v_fmac_f32_e32 v142, v147, v146
	v_add_f32_e32 v144, 1.0, v144
	v_fma_f32 v134, -v145, v142, v134
	v_div_scale_f32 v145, s[2:3], v144, v144, 1.0
	v_rcp_f32_e32 v147, v145
	v_div_fmas_f32 v134, v134, v146, v142
	v_div_fixup_f32 v134, v134, v143, 1.0
	v_mul_f32_e32 v143, 0xbfb8aa3b, v64
	global_store_dword v[140:141], v134, off offset:2304
	v_fma_f32 v134, -v145, v147, 1.0
	v_exp_f32_e32 v143, v143
; DI float sigmoid_f(float z) { return 1.f / (1.f + __expf(-z)); }
; DI void gemm1_tile(const Params& p, GemmRegs<ALoadBf16>& G, bool pre, int tm, int tn, bool has_next, int tmn, int tnn, char* sm) {
;     ...
;         if (wn == 0 && r < 24) {
;             float* gb = (float*)(p.ws + WS_GATES) + rall * 24 + r;
; #pragma unroll
;             for (int mi = 0; mi < 2; ++mi)
; #pragma unroll
;                 for (int i = 0; i < 16; ++i) gb[(mi * 32 + (i & 3) + 8 * (i >> 2)) * 24] = sigmoid_f(acc[mi][0][i]);
;         }
	v_fmac_f32_e32 v147, v134, v147
	v_div_scale_f32 v134, vcc, 1.0, v144, 1.0
	v_mul_f32_e32 v142, v134, v147
	v_fma_f32 v146, -v145, v142, v134
	v_fmac_f32_e32 v142, v146, v147
	v_add_f32_e32 v143, 1.0, v143
	v_fma_f32 v134, -v145, v142, v134
	v_div_scale_f32 v145, s[2:3], v143, v143, 1.0
	v_rcp_f32_e32 v146, v145
	v_div_fmas_f32 v134, v134, v147, v142
	v_div_fixup_f32 v134, v134, v144, 1.0
	v_mul_f32_e32 v144, 0xbfb8aa3b, v65
	global_store_dword v[140:141], v134, off offset:2400
	v_fma_f32 v134, -v145, v146, 1.0
	v_exp_f32_e32 v144, v144
	v_fmac_f32_e32 v146, v134, v146
	v_div_scale_f32 v134, vcc, 1.0, v143, 1.0
	v_mul_f32_e32 v142, v134, v146
	v_fma_f32 v147, -v145, v142, v134
	v_fmac_f32_e32 v142, v147, v146
	v_add_f32_e32 v144, 1.0, v144
	v_fma_f32 v134, -v145, v142, v134
	v_div_scale_f32 v145, s[2:3], v144, v144, 1.0
	v_rcp_f32_e32 v147, v145
	v_div_fmas_f32 v134, v134, v146, v142
	v_div_fixup_f32 v134, v134, v143, 1.0
	v_mul_f32_e32 v143, 0xbfb8aa3b, v18
	global_store_dword v[140:141], v134, off offset:2496
	v_fma_f32 v134, -v145, v147, 1.0
	v_exp_f32_e32 v143, v143
	v_fmac_f32_e32 v147, v134, v147
	v_div_scale_f32 v134, vcc, 1.0, v144, 1.0
	v_mul_f32_e32 v142, v134, v147
	v_fma_f32 v146, -v145, v142, v134
	v_fmac_f32_e32 v142, v146, v147
	v_add_f32_e32 v143, 1.0, v143
	v_fma_f32 v134, -v145, v142, v134
	v_div_scale_f32 v145, s[2:3], v143, v143, 1.0
	v_rcp_f32_e32 v146, v145
	v_div_fmas_f32 v134, v134, v147, v142
	v_div_fixup_f32 v134, v134, v144, 1.0
	v_mul_f32_e32 v144, 0xbfb8aa3b, v19
	global_store_dword v[140:141], v134, off offset:2592
	v_fma_f32 v134, -v145, v146, 1.0
	v_exp_f32_e32 v144, v144
	v_fmac_f32_e32 v146, v134, v146
	v_div_scale_f32 v134, vcc, 1.0, v143, 1.0
	v_mul_f32_e32 v142, v134, v146
	v_fma_f32 v147, -v145, v142, v134
	v_fmac_f32_e32 v142, v147, v146
	v_add_f32_e32 v144, 1.0, v144
	v_fma_f32 v134, -v145, v142, v134
	v_div_scale_f32 v145, s[2:3], v144, v144, 1.0
	v_rcp_f32_e32 v147, v145
	v_div_fmas_f32 v134, v134, v146, v142
	v_div_fixup_f32 v134, v134, v143, 1.0
	v_mul_f32_e32 v143, 0xbfb8aa3b, v20
	global_store_dword v[140:141], v134, off offset:3072
	v_fma_f32 v134, -v145, v147, 1.0
	v_exp_f32_e32 v143, v143
	v_fmac_f32_e32 v147, v134, v147
	v_div_scale_f32 v134, vcc, 1.0, v144, 1.0
	v_mul_f32_e32 v142, v134, v147
	v_fma_f32 v146, -v145, v142, v134
	v_fmac_f32_e32 v142, v146, v147
	v_add_f32_e32 v143, 1.0, v143
	v_fma_f32 v134, -v145, v142, v134
	v_div_scale_f32 v145, s[2:3], v143, v143, 1.0
	v_rcp_f32_e32 v146, v145
	v_div_fmas_f32 v134, v134, v147, v142
	v_div_fixup_f32 v134, v134, v144, 1.0
	v_mul_f32_e32 v144, 0xbfb8aa3b, v21
	global_store_dword v[140:141], v134, off offset:3168
	v_fma_f32 v134, -v145, v146, 1.0
	v_exp_f32_e32 v144, v144
	v_fmac_f32_e32 v146, v134, v146
	v_div_scale_f32 v134, vcc, 1.0, v143, 1.0
	v_mul_f32_e32 v142, v134, v146
	v_fma_f32 v147, -v145, v142, v134
	v_fmac_f32_e32 v142, v147, v146
	v_add_f32_e32 v144, 1.0, v144
	v_fma_f32 v134, -v145, v142, v134
	v_div_scale_f32 v145, s[2:3], v144, v144, 1.0
	v_rcp_f32_e32 v147, v145
	v_div_fmas_f32 v134, v134, v146, v142
	v_div_fixup_f32 v134, v134, v143, 1.0
	v_mul_f32_e32 v143, 0xbfb8aa3b, v22
	global_store_dword v[140:141], v134, off offset:3264
	v_fma_f32 v134, -v145, v147, 1.0
	v_exp_f32_e32 v143, v143
	v_fmac_f32_e32 v147, v134, v147
	v_div_scale_f32 v134, vcc, 1.0, v144, 1.0
	v_mul_f32_e32 v142, v134, v147
	v_fma_f32 v146, -v145, v142, v134
	v_fmac_f32_e32 v142, v146, v147
	v_add_f32_e32 v143, 1.0, v143
	v_fma_f32 v134, -v145, v142, v134
	v_div_scale_f32 v145, s[2:3], v143, v143, 1.0
	v_rcp_f32_e32 v146, v145
	v_div_fmas_f32 v134, v134, v147, v142
	v_div_fixup_f32 v134, v134, v144, 1.0
	v_mul_f32_e32 v144, 0xbfb8aa3b, v23
	global_store_dword v[140:141], v134, off offset:3360
	v_fma_f32 v134, -v145, v146, 1.0
	v_exp_f32_e32 v144, v144
	v_fmac_f32_e32 v146, v134, v146
	v_div_scale_f32 v134, vcc, 1.0, v143, 1.0
	v_mul_f32_e32 v142, v134, v146
	v_fma_f32 v147, -v145, v142, v134
	v_fmac_f32_e32 v142, v147, v146
	v_add_f32_e32 v144, 1.0, v144
	v_fma_f32 v134, -v145, v142, v134
	v_div_scale_f32 v145, s[2:3], v144, v144, 1.0
	v_rcp_f32_e32 v147, v145
	v_div_fmas_f32 v134, v134, v146, v142
	v_div_fixup_f32 v134, v134, v143, 1.0
	v_mul_f32_e32 v143, 0xbfb8aa3b, v24
	global_store_dword v[140:141], v134, off offset:3840
	v_fma_f32 v134, -v145, v147, 1.0
	v_exp_f32_e32 v143, v143
	v_fmac_f32_e32 v147, v134, v147
	v_div_scale_f32 v134, vcc, 1.0, v144, 1.0
	v_mul_f32_e32 v142, v134, v147
	v_fma_f32 v146, -v145, v142, v134
	v_fmac_f32_e32 v142, v146, v147
	v_add_f32_e32 v143, 1.0, v143
	v_fma_f32 v134, -v145, v142, v134
	v_div_scale_f32 v145, s[2:3], v143, v143, 1.0
	v_rcp_f32_e32 v146, v145
	v_div_fmas_f32 v134, v134, v147, v142
	v_div_fixup_f32 v134, v134, v144, 1.0
	v_mul_f32_e32 v144, 0xbfb8aa3b, v25
	global_store_dword v[140:141], v134, off offset:3936
	v_fma_f32 v134, -v145, v146, 1.0
	v_exp_f32_e32 v144, v144
	v_fmac_f32_e32 v146, v134, v146
	v_div_scale_f32 v134, vcc, 1.0, v143, 1.0
	v_mul_f32_e32 v142, v134, v146
	v_fma_f32 v147, -v145, v142, v134
	v_fmac_f32_e32 v142, v147, v146
; DI float sigmoid_f(float z) { return 1.f / (1.f + __expf(-z)); }
; DI void gemm1_tile(const Params& p, GemmRegs<ALoadBf16>& G, bool pre, int tm, int tn, bool has_next, int tmn, int tnn, char* sm) {
;     ...
;         if (wn == 0 && r < 24) {
;             float* gb = (float*)(p.ws + WS_GATES) + rall * 24 + r;
; #pragma unroll
;             for (int mi = 0; mi < 2; ++mi)
; #pragma unroll
;                 for (int i = 0; i < 16; ++i) gb[(mi * 32 + (i & 3) + 8 * (i >> 2)) * 24] = sigmoid_f(acc[mi][0][i]);
;         }
	v_add_f32_e32 v144, 1.0, v144
	v_fma_f32 v134, -v145, v142, v134
	v_div_scale_f32 v145, s[2:3], v144, v144, 1.0
	v_rcp_f32_e32 v147, v145
	v_div_fmas_f32 v134, v134, v146, v142
	v_div_fixup_f32 v134, v134, v143, 1.0
	global_store_dword v[140:141], v134, off offset:4032
	v_fma_f32 v134, -v145, v147, 1.0
	v_fmac_f32_e32 v147, v134, v147
	v_div_scale_f32 v134, vcc, 1.0, v144, 1.0
	v_mul_f32_e32 v142, v134, v147
	v_fma_f32 v143, -v145, v142, v134
	v_fmac_f32_e32 v142, v143, v147
	v_mul_f32_e32 v143, 0xbfb8aa3b, v26
	v_exp_f32_e32 v143, v143
	v_fma_f32 v134, -v145, v142, v134
	v_div_fmas_f32 v134, v134, v147, v142
	v_div_fixup_f32 v134, v134, v144, 1.0
	v_add_f32_e32 v142, 1.0, v143
	v_div_scale_f32 v143, s[2:3], v142, v142, 1.0
	v_rcp_f32_e32 v144, v143
	v_add_co_u32_e32 v140, vcc, s75, v140
	v_mul_f32_e32 v146, 0xbfb8aa3b, v27
	s_nop 0
	v_addc_co_u32_e32 v141, vcc, 0, v141, vcc
	global_store_dword v[140:141], v134, off offset:32
	v_fma_f32 v134, -v143, v144, 1.0
	v_fmac_f32_e32 v144, v134, v144
	v_div_scale_f32 v134, vcc, 1.0, v142, 1.0
	v_exp_f32_e32 v146, v146
	v_mul_f32_e32 v145, v134, v144
	v_fma_f32 v147, -v143, v145, v134
	v_fmac_f32_e32 v145, v147, v144
	v_fma_f32 v134, -v143, v145, v134
	v_add_f32_e32 v143, 1.0, v146
	v_div_scale_f32 v146, s[2:3], v143, v143, 1.0
	v_rcp_f32_e32 v147, v146
	v_div_fmas_f32 v134, v134, v144, v145
	v_mul_f32_e32 v144, 0xbfb8aa3b, v28
	v_div_fixup_f32 v134, v134, v142, 1.0
	v_exp_f32_e32 v144, v144
	global_store_dword v[140:141], v134, off offset:512
	v_fma_f32 v134, -v146, v147, 1.0
	v_fmac_f32_e32 v147, v134, v147
	v_div_scale_f32 v134, vcc, 1.0, v143, 1.0
	v_mul_f32_e32 v142, v134, v147
	v_fma_f32 v145, -v146, v142, v134
	v_add_f32_e32 v144, 1.0, v144
	v_fmac_f32_e32 v142, v145, v147
	v_div_scale_f32 v145, s[2:3], v144, v144, 1.0
	v_fma_f32 v134, -v146, v142, v134
	v_rcp_f32_e32 v146, v145
	v_div_fmas_f32 v134, v134, v147, v142
	v_div_fixup_f32 v134, v134, v143, 1.0
	v_mul_f32_e32 v143, 0xbfb8aa3b, v29
	global_store_dword v[140:141], v134, off offset:608
	v_fma_f32 v134, -v145, v146, 1.0
	v_exp_f32_e32 v143, v143
	v_fmac_f32_e32 v146, v134, v146
	v_div_scale_f32 v134, vcc, 1.0, v144, 1.0
	v_mul_f32_e32 v142, v134, v146
	v_fma_f32 v147, -v145, v142, v134
	v_fmac_f32_e32 v142, v147, v146
	v_add_f32_e32 v143, 1.0, v143
	v_fma_f32 v134, -v145, v142, v134
	v_div_scale_f32 v145, s[2:3], v143, v143, 1.0
	v_rcp_f32_e32 v147, v145
	v_div_fmas_f32 v134, v134, v146, v142
	v_div_fixup_f32 v134, v134, v144, 1.0
	v_mul_f32_e32 v144, 0xbfb8aa3b, v30
	global_store_dword v[140:141], v134, off offset:704
	v_fma_f32 v134, -v145, v147, 1.0
	v_exp_f32_e32 v144, v144
	v_fmac_f32_e32 v147, v134, v147
	v_div_scale_f32 v134, vcc, 1.0, v143, 1.0
	v_mul_f32_e32 v142, v134, v147
	v_fma_f32 v146, -v145, v142, v134
	v_fmac_f32_e32 v142, v146, v147
	v_add_f32_e32 v144, 1.0, v144
	v_fma_f32 v134, -v145, v142, v134
	v_div_scale_f32 v145, s[2:3], v144, v144, 1.0
	v_rcp_f32_e32 v146, v145
	v_div_fmas_f32 v134, v134, v147, v142
	v_div_fixup_f32 v134, v134, v143, 1.0
	v_mul_f32_e32 v143, 0xbfb8aa3b, v31
	global_store_dword v[140:141], v134, off offset:800
	v_fma_f32 v134, -v145, v146, 1.0
	v_exp_f32_e32 v143, v143
	v_fmac_f32_e32 v146, v134, v146
	v_div_scale_f32 v134, vcc, 1.0, v144, 1.0
	v_mul_f32_e32 v142, v134, v146
	v_fma_f32 v147, -v145, v142, v134
	v_fmac_f32_e32 v142, v147, v146
	v_add_f32_e32 v143, 1.0, v143
	v_fma_f32 v134, -v145, v142, v134
	v_div_scale_f32 v145, s[2:3], v143, v143, 1.0
	v_rcp_f32_e32 v147, v145
	v_div_fmas_f32 v134, v134, v146, v142
	v_div_fixup_f32 v134, v134, v144, 1.0
	v_mul_f32_e32 v144, 0xbfb8aa3b, v32
	global_store_dword v[140:141], v134, off offset:1280
	v_fma_f32 v134, -v145, v147, 1.0
	v_exp_f32_e32 v144, v144
	v_fmac_f32_e32 v147, v134, v147
	v_div_scale_f32 v134, vcc, 1.0, v143, 1.0
	v_mul_f32_e32 v142, v134, v147
	v_fma_f32 v146, -v145, v142, v134
	v_fmac_f32_e32 v142, v146, v147
	v_add_f32_e32 v144, 1.0, v144
	v_fma_f32 v134, -v145, v142, v134
	v_div_scale_f32 v145, s[2:3], v144, v144, 1.0
	v_rcp_f32_e32 v146, v145
	v_div_fmas_f32 v134, v134, v147, v142
	v_div_fixup_f32 v134, v134, v143, 1.0
	v_mul_f32_e32 v143, 0xbfb8aa3b, v33
	global_store_dword v[140:141], v134, off offset:1376
	v_fma_f32 v134, -v145, v146, 1.0
	v_exp_f32_e32 v143, v143
	v_fmac_f32_e32 v146, v134, v146
	v_div_scale_f32 v134, vcc, 1.0, v144, 1.0
	v_mul_f32_e32 v142, v134, v146
	v_fma_f32 v147, -v145, v142, v134
	v_fmac_f32_e32 v142, v147, v146
	v_add_f32_e32 v143, 1.0, v143
	v_fma_f32 v134, -v145, v142, v134
	v_div_scale_f32 v145, s[2:3], v143, v143, 1.0
	v_rcp_f32_e32 v147, v145
	v_div_fmas_f32 v134, v134, v146, v142
	v_div_fixup_f32 v134, v134, v144, 1.0
	global_store_dword v[140:141], v134, off offset:1472
	v_fma_f32 v134, -v145, v147, 1.0
	v_fmac_f32_e32 v147, v134, v147
	v_div_scale_f32 v134, vcc, 1.0, v143, 1.0
	v_mul_f32_e32 v142, v134, v147
	v_fma_f32 v144, -v145, v142, v134
	v_fmac_f32_e32 v142, v144, v147
	v_fma_f32 v134, -v145, v142, v134
	v_div_fmas_f32 v134, v134, v147, v142
	v_div_fixup_f32 v134, v134, v143, 1.0
	global_store_dword v[140:141], v134, off offset:1568

; DI float fexp2(float x) { return __builtin_amdgcn_exp2f(x); }
; DI f32x16 mfma32(bf16x8 a, bf16x8 b, f32x16 c) { return __builtin_amdgcn_mfma_f32_32x32x16_bf16(a, b, c, 0, 0, 0); }
; DI f32x16 zero16() { f32x16 z; for (int i = 0; i < 16; ++i) z[i] = 0.f; return z; }
; template <int MASK, bool NEAR, int PASS>
; DI void flash_tile(Flash& st, const bf16x8 (&qf)[4], const char* kbuf, const char* vbuf, int pos0, int qpos, bool on,
;                    const float* lut, float bfar, float* imp_row, float rinv) {
;     ...
;     for (int ks = 0; ks < 4; ++ks) {
;         const int ka = r * 128 + (((2 * ks + h) ^ ((r >> 1) & 7)) << 4);
;         const bf16x8 a0 = *(const bf16x8*)(kbuf + ka);
;         const bf16x8 a1 = *(const bf16x8*)(kbuf + 4096 + ka);
;         s[0] = mfma32(a0, qf[ks], s[0]);
;         s[1] = mfma32(a1, qf[ks], s[1]);
;     }
;     constexpr float c1 = 0.125f * LOG2E;
;     float alpha = 1.f;
;     float rs = 0.f;
;     if (!NEAR) {
;         const float bc = MASK == 2 ? 0.f : bfar;
;         float mref;
;         if (PASS != 2) {
;             float mr = s[0][0];
; #pragma unroll
;             for (int i = 1; i < 16; ++i) mr = fmaxf(mr, s[0][i]);
; #pragma unroll
;             for (int i = 0; i < 16; ++i) mr = fmaxf(mr, s[1][i]);
;             float mx = on ? mr * c1 + bc : -1e30f;
;             mx = fmaxf(mx, __shfl_xor(mx, 32));
;             const float mnew = fmaxf(st.m, mx);
;             alpha = fexp2(st.m - mnew);
;             st.m = mnew;
;             mref = mnew;
;         } else mref = st.m;
;         float bm = on ? bc - mref : -1e30f;
;         if (PASS == 2) bm = on ? bm + __log2f(rinv) : -1e30f;
; #pragma unroll
;         for (int tt = 0; tt < 2; ++tt)
; #pragma unroll
;             for (int i = 0; i < 16; ++i) { const float pv = fexp2(s[tt][i] * c1 + bm); s[tt][i] = pv; rs += pv; }
;     ...
;     if (PASS != 2) {
;         rs += __shfl_xor(rs, 32);
;         st.l = st.l * alpha + rs;
;     }
;     f32x16 ia = zero16();
;     if (PASS != 1) {
;         if (PASS == 0) {
; #pragma unroll
;             for (int i = 0; i < 16; ++i) { st.o0[i] *= alpha; st.o1[i] *= alpha; }
;         }
.LBB0_1094:
	s_waitcnt lgkmcnt(0)
	v_ashrrev_i32_e32 v38, 6, v52
	v_cmp_gt_i32_e32 vcc, 64, v38
	s_nop 1
	v_cndmask_b32_e32 v37, v154, v178, vcc
	v_cndmask_b32_e32 v36, v177, v179, vcc
	v_lshrrev_b64 v[36:37], v38, v[36:37]
	v_and_b32_e32 v36, 1, v36
	v_cmp_eq_u32_e32 vcc, 1, v36
	s_and_b64 s[2:3], s[8:9], vcc
	v_cndmask_b32_e64 v36, 0, 1, s[2:3]
	v_cndmask_b32_e64 v37, 0, 1, s[8:9]
	v_cmp_lt_i32_e32 vcc, s86, v38
	s_nop 1
	v_cndmask_b32_e32 v36, v36, v37, vcc
	v_and_b32_e32 v36, 1, v36
	v_cmp_eq_u32_e64 s[16:17], 1, v36
	v_cmp_ne_u32_e32 vcc, 0, v36
	s_cbranch_vccz .LBB0_1084
	v_add_u32_e32 v40, s24, v190
	ds_read_b128 v[36:39], v40
	ds_read_b128 v[138:141], v40 offset:4096
	v_add_u32_e32 v40, s24, v191
	ds_read_b128 v[150:153], v40
	ds_read_b128 v[134:137], v40 offset:4096
	v_add_u32_e32 v40, s24, v192
	ds_read_b128 v[146:149], v40
	ds_read_b128 v[130:133], v40 offset:4096
	v_add_u32_e32 v40, s24, v193
	ds_read_b128 v[142:145], v40
	ds_read_b128 v[126:129], v40 offset:4096
	v_cmp_le_i32_e32 vcc, v52, v169
	v_add3_u32 v181, s24, v199, v200
	s_and_saveexec_b64 s[2:3], vcc
	s_xor_b64 s[2:3], exec, s[2:3]
	s_cbranch_execz .LBB0_1097
	s_waitcnt lgkmcnt(7)
	v_mfma_f32_32x32x16_bf16 v[52:67], v[36:39], v[94:97], 0
	s_waitcnt lgkmcnt(5)
	v_mfma_f32_32x32x16_bf16 v[52:67], v[150:153], v[98:101], v[52:67]
	v_mfma_f32_32x32x16_bf16 v[36:51], v[138:141], v[94:97], 0
	s_waitcnt lgkmcnt(3)
	v_mfma_f32_32x32x16_bf16 v[52:67], v[146:149], v[102:105], v[52:67]
	v_mfma_f32_32x32x16_bf16 v[36:51], v[134:137], v[98:101], v[36:51]
	s_waitcnt lgkmcnt(1)
	v_mfma_f32_32x32x16_bf16 v[52:67], v[142:145], v[106:109], v[52:67]
	v_mfma_f32_32x32x16_bf16 v[36:51], v[130:133], v[102:105], v[36:51]
	s_nop 10
	v_max_f32_e32 v134, v53, v53
	v_max_f32_e32 v135, v52, v52
	v_max_f32_e32 v134, v135, v134
	v_max3_f32 v130, v134, v54, v55
	v_max3_f32 v130, v130, v56, v57
	v_max3_f32 v130, v130, v58, v59
	v_max3_f32 v130, v130, v60, v61
	s_waitcnt lgkmcnt(0)
	v_mfma_f32_32x32x16_bf16 v[36:51], v[126:129], v[106:109], v[36:51]
	v_max3_f32 v130, v130, v62, v63
	v_max3_f32 v130, v130, v64, v65
	v_max3_f32 v130, v130, v66, v67
	s_nop 8
	v_max3_f32 v126, v130, v36, v37
	v_max3_f32 v126, v126, v38, v39
	v_max3_f32 v126, v126, v40, v41
	v_max3_f32 v126, v126, v42, v43
	v_max3_f32 v126, v126, v44, v45
	v_max3_f32 v126, v126, v46, v47
	v_max3_f32 v126, v126, v48, v49
	v_max3_f32 v126, v126, v50, v51
	v_fmamk_f32 v126, v126, 0x3e38aa3b, v224
	v_cndmask_b32_e64 v126, v215, v126, s[16:17]
	v_mov_b32_e32 v127, v126
	s_nop 1
	v_permlane32_swap_b32_e32 v126, v127
	v_max3_f32 v126, v182, v126, v127
	s_mov_b32 s99, 0x41000000
	v_sub_f32_e32 v127, v126, v182
	v_cmp_lt_f32_e64 s[100:101], s99, v127
	v_cndmask_b32_e64 v126, v182, v126, s[100:101]
	v_sub_f32_e32 v128, v224, v126
	v_cndmask_b32_e64 v128, v215, v128, s[16:17]
	v_fmamk_f32 v52, v52, 0x3e38aa3b, v128
	v_exp_f32_e32 v129, v52
	v_fmamk_f32 v52, v53, 0x3e38aa3b, v128
	v_exp_f32_e32 v53, v52
	v_fmamk_f32 v52, v54, 0x3e38aa3b, v128
	v_exp_f32_e32 v54, v52
	v_fmamk_f32 v52, v55, 0x3e38aa3b, v128
	v_exp_f32_e32 v55, v52
	v_fmamk_f32 v52, v56, 0x3e38aa3b, v128
	v_exp_f32_e32 v56, v52
	v_fmamk_f32 v52, v57, 0x3e38aa3b, v128
	v_exp_f32_e32 v57, v52
	v_fmamk_f32 v52, v58, 0x3e38aa3b, v128
	v_exp_f32_e32 v58, v52
	v_fmamk_f32 v52, v59, 0x3e38aa3b, v128
	v_exp_f32_e32 v59, v52
	v_fmamk_f32 v52, v60, 0x3e38aa3b, v128
	v_exp_f32_e32 v60, v52
	v_fmamk_f32 v52, v61, 0x3e38aa3b, v128
	v_exp_f32_e32 v61, v52
	v_fmamk_f32 v52, v62, 0x3e38aa3b, v128
	v_exp_f32_e32 v62, v52
	v_fmamk_f32 v52, v63, 0x3e38aa3b, v128
	v_exp_f32_e32 v63, v52
	v_fmamk_f32 v52, v64, 0x3e38aa3b, v128
	v_exp_f32_e32 v64, v52
	v_fmamk_f32 v52, v65, 0x3e38aa3b, v128
	v_exp_f32_e32 v65, v52
	v_fmamk_f32 v52, v66, 0x3e38aa3b, v128
	v_fmamk_f32 v66, v67, 0x3e38aa3b, v128
	v_exp_f32_e32 v67, v52
	v_add_f32_e32 v52, 0, v129
	v_add_f32_e32 v52, v53, v52
	v_add_f32_e32 v52, v54, v52
	v_add_f32_e32 v52, v55, v52
	v_add_f32_e32 v52, v56, v52
	v_add_f32_e32 v52, v57, v52
	v_add_f32_e32 v52, v58, v52
	v_add_f32_e32 v52, v59, v52
	v_add_f32_e32 v52, v60, v52
	v_add_f32_e32 v52, v61, v52
	v_add_f32_e32 v52, v62, v52
	v_add_f32_e32 v52, v63, v52
	v_exp_f32_e32 v66, v66
	v_fmamk_f32 v36, v36, 0x3e38aa3b, v128
	v_add_f32_e32 v52, v64, v52
	v_exp_f32_e32 v130, v36
	v_fmamk_f32 v36, v37, 0x3e38aa3b, v128
	v_add_f32_e32 v52, v65, v52
	v_exp_f32_e32 v131, v36
	v_fmamk_f32 v36, v38, 0x3e38aa3b, v128
	v_add_f32_e32 v52, v67, v52
	v_exp_f32_e32 v132, v36
	v_fmamk_f32 v36, v39, 0x3e38aa3b, v128
	v_add_f32_e32 v52, v66, v52
	v_exp_f32_e32 v133, v36
	v_fmamk_f32 v37, v40, 0x3e38aa3b, v128
	v_add_f32_e32 v36, v130, v52
	v_exp_f32_e32 v134, v37
	v_fmamk_f32 v37, v41, 0x3e38aa3b, v128
	v_add_f32_e32 v36, v131, v36
	v_exp_f32_e32 v135, v37
	v_fmamk_f32 v37, v42, 0x3e38aa3b, v128
	v_add_f32_e32 v36, v132, v36
	v_exp_f32_e32 v136, v37
	v_fmamk_f32 v37, v43, 0x3e38aa3b, v128
	v_add_f32_e32 v36, v133, v36
	v_exp_f32_e32 v137, v37
	v_fmamk_f32 v37, v44, 0x3e38aa3b, v128
	v_add_f32_e32 v36, v134, v36
	v_exp_f32_e32 v138, v37
	v_fmamk_f32 v37, v45, 0x3e38aa3b, v128
	v_add_f32_e32 v36, v135, v36
	v_exp_f32_e32 v139, v37
	v_fmamk_f32 v37, v46, 0x3e38aa3b, v128
	v_add_f32_e32 v36, v136, v36
	v_exp_f32_e32 v140, v37
	v_add_f32_e32 v36, v137, v36
	v_add_f32_e32 v36, v138, v36
	v_sub_f32_e32 v127, v182, v126
	v_add_f32_e32 v36, v139, v36
	v_exp_f32_e32 v52, v127
	v_add_f32_e32 v127, v140, v36
	v_fmamk_f32 v36, v47, 0x3e38aa3b, v128
	v_exp_f32_e32 v141, v36
	ds_read_b64_tr_b16 v[36:37], v181 offset:8192
	ds_read_b64_tr_b16 v[38:39], v181 offset:9216
	ds_read_b64_tr_b16 v[46:47], v181 offset:9280
	ds_read_b64_tr_b16 v[44:45], v181 offset:8256
	v_cvt_pk_bf16_f32 v43, v58, v59
	v_cvt_pk_bf16_f32 v42, v56, v57
	v_cvt_pk_bf16_f32 v41, v54, v55
	v_cvt_pk_bf16_f32 v40, v129, v53
	s_cmp_eq_u64 s[100:101], 0
	s_cbranch_scc1 .Llz_gatA
	v_pk_mul_f32 v[34:35], v[34:35], v[52:53] op_sel_hi:[1,0]
	v_pk_mul_f32 v[32:33], v[32:33], v[52:53] op_sel_hi:[1,0]
	v_pk_mul_f32 v[30:31], v[30:31], v[52:53] op_sel_hi:[1,0]
	v_pk_mul_f32 v[28:29], v[28:29], v[52:53] op_sel_hi:[1,0]
	v_pk_mul_f32 v[26:27], v[26:27], v[52:53] op_sel_hi:[1,0]
	v_pk_mul_f32 v[24:25], v[24:25], v[52:53] op_sel_hi:[1,0]
	v_pk_mul_f32 v[22:23], v[22:23], v[52:53] op_sel_hi:[1,0]
	v_pk_mul_f32 v[20:21], v[20:21], v[52:53] op_sel_hi:[1,0]
	v_pk_mul_f32 v[18:19], v[18:19], v[52:53] op_sel_hi:[1,0]
	v_pk_mul_f32 v[16:17], v[16:17], v[52:53] op_sel_hi:[1,0]
	v_pk_mul_f32 v[14:15], v[14:15], v[52:53] op_sel_hi:[1,0]
	v_pk_mul_f32 v[12:13], v[12:13], v[52:53] op_sel_hi:[1,0]
	v_pk_mul_f32 v[10:11], v[10:11], v[52:53] op_sel_hi:[1,0]
	v_pk_mul_f32 v[8:9], v[8:9], v[52:53] op_sel_hi:[1,0]
	v_pk_mul_f32 v[6:7], v[6:7], v[52:53] op_sel_hi:[1,0]
	v_pk_mul_f32 v[4:5], v[4:5], v[52:53] op_sel_hi:[1,0]
	s_nop 1
; DI f32x16 mfma32(bf16x8 a, bf16x8 b, f32x16 c) { return __builtin_amdgcn_mfma_f32_32x32x16_bf16(a, b, c, 0, 0, 0); }
; DI int opaque(int v) { asm volatile("" : "+v"(v)); return v; }
; template <int MASK, bool NEAR, int PASS>
; DI void flash_tile(Flash& st, const bf16x8 (&qf)[4], const char* kbuf, const char* vbuf, int pos0, int qpos, bool on,
;                    const float* lut, float bfar, float* imp_row, float rinv) {
;     ...
;     if (PASS != 2) {
;         rs += __shfl_xor(rs, 32);
;         st.l = st.l * alpha + rs;
;     }
;     ...
;         const int G = lane >> 4, i16 = lane & 15, q = i16 >> 2, pp = i16 & 3;
;         const char* vb = vbuf + (4 * (G >> 1) + q) * 128 + (16 * (G & 1) + 4 * pp) * 2;
; #pragma unroll
;         for (int tt = 0; tt < 2; ++tt)
; #pragma unroll
;             for (int ss = 0; ss < 2; ++ss) {
;                 f32x4 pa = {s[tt][8 * ss], s[tt][8 * ss + 1], s[tt][8 * ss + 2], s[tt][8 * ss + 3]};
;                 f32x4 pb2 = {s[tt][8 * ss + 4], s[tt][8 * ss + 5], s[tt][8 * ss + 6], s[tt][8 * ss + 7]};
;                 const bf16x8 pfrag = cvt8(pa, pb2);
;                 const char* vk = vb + (32 * tt + 16 * ss) * 128;
;                 if (PASS == 2) {
;                     const int d = opaque((lane & 31) - h) - (8 * tt + 4 * ss);
;                     const unsigned one2 = 0x3F803F80u, oneh = 0x3F800000u;
;                     const uint4 ov = {d == 0 ? one2 : 0u, d == 0 ? one2 : (d == 1 ? oneh : 0u), d == 2 ? one2 : 0u, d == 2 ? one2 : (d == 3 ? oneh : 0u)};
;                     ia = mfma32(__builtin_bit_cast(bf16x8, ov), pfrag, ia);
;                 }
;                 {
;                     const s16x4 lo = tr_read(vk), hi = tr_read(vk + 8 * 128);
;                     const bf16x8 va = __builtin_shufflevector(lo, hi, 0, 1, 2, 3, 4, 5, 6, 7);
;                     st.o0 = mfma32(va, pfrag, st.o0);
;                 }
;                 {
;                     const s16x4 lo = tr_read(vk + 64), hi = tr_read(vk + 8 * 128 + 64);
;                     const bf16x8 va = __builtin_shufflevector(lo, hi, 0, 1, 2, 3, 4, 5, 6, 7);
;                     st.o1 = mfma32(va, pfrag, st.o1);
;                 }
;             }
.Llz_gatA:
	s_waitcnt lgkmcnt(2)
	v_mfma_f32_32x32x16_bf16 v[20:35], v[36:39], v[40:43], v[20:35]
	ds_read_b64_tr_b16 v[36:37], v181 offset:10240
	ds_read_b64_tr_b16 v[38:39], v181 offset:11264
	v_fmamk_f32 v50, v50, 0x3e38aa3b, v128
	v_exp_f32_e32 v50, v50
	v_add_f32_e32 v53, v141, v127
	v_mov_b32_e32 v182, v126
	s_waitcnt lgkmcnt(2)
	v_mfma_f32_32x32x16_bf16 v[4:19], v[44:47], v[40:43], v[4:19]
	ds_read_b64_tr_b16 v[46:47], v181 offset:11328
	ds_read_b64_tr_b16 v[44:45], v181 offset:10304
	v_cvt_pk_bf16_f32 v43, v67, v66
	v_cvt_pk_bf16_f32 v42, v64, v65
	v_cvt_pk_bf16_f32 v41, v62, v63
	v_cvt_pk_bf16_f32 v40, v60, v61
	s_waitcnt lgkmcnt(2)
	s_nop 0
	v_mfma_f32_32x32x16_bf16 v[20:35], v[36:39], v[40:43], v[20:35]
	v_fmamk_f32 v36, v48, 0x3e38aa3b, v128
	v_exp_f32_e32 v48, v36
	v_fmamk_f32 v36, v49, 0x3e38aa3b, v128
	v_exp_f32_e32 v49, v36
	ds_read_b64_tr_b16 v[36:37], v181 offset:12288
	ds_read_b64_tr_b16 v[38:39], v181 offset:13312
	v_fmac_f32_e32 v128, 0x3e38aa3b, v51
	v_exp_f32_e32 v51, v128
	s_waitcnt lgkmcnt(2)
	v_mfma_f32_32x32x16_bf16 v[4:19], v[44:47], v[40:43], v[4:19]
	ds_read_b64_tr_b16 v[46:47], v181 offset:13376
	ds_read_b64_tr_b16 v[44:45], v181 offset:12352
	v_cvt_pk_bf16_f32 v43, v136, v137
	v_cvt_pk_bf16_f32 v42, v134, v135
	v_cvt_pk_bf16_f32 v41, v132, v133
	v_cvt_pk_bf16_f32 v40, v130, v131
	s_waitcnt lgkmcnt(2)
	s_nop 0
	v_mfma_f32_32x32x16_bf16 v[20:35], v[36:39], v[40:43], v[20:35]
	v_add_f32_e32 v36, v48, v53
	v_add_f32_e32 v36, v49, v36
	v_add_f32_e32 v53, v50, v36
	ds_read_b64_tr_b16 v[36:37], v181 offset:14336
	ds_read_b64_tr_b16 v[38:39], v181 offset:15360
	v_add_f32_e32 v53, v51, v53
	s_waitcnt lgkmcnt(2)
	v_mfma_f32_32x32x16_bf16 v[4:19], v[44:47], v[40:43], v[4:19]
	ds_read_b64_tr_b16 v[46:47], v181 offset:15424
	ds_read_b64_tr_b16 v[44:45], v181 offset:14400
	v_cvt_pk_bf16_f32 v43, v50, v51
	v_cvt_pk_bf16_f32 v42, v48, v49
	v_cvt_pk_bf16_f32 v41, v140, v141
	v_cvt_pk_bf16_f32 v40, v138, v139
	s_waitcnt lgkmcnt(2)
	s_nop 0
	v_mfma_f32_32x32x16_bf16 v[20:35], v[36:39], v[40:43], v[20:35]
	v_mov_b32_e32 v36, v53
	s_nop 1
	v_permlane32_swap_b32_e32 v53, v36
	v_add_f32_e32 v36, v53, v36
	s_waitcnt lgkmcnt(0)
	v_fmac_f32_e32 v36, v180, v52
	v_mfma_f32_32x32x16_bf16 v[4:19], v[44:47], v[40:43], v[4:19]
	v_mov_b32_e32 v180, v36

; DI float fexp2(float x) { return __builtin_amdgcn_exp2f(x); }
; DI f32x16 mfma32(bf16x8 a, bf16x8 b, f32x16 c) { return __builtin_amdgcn_mfma_f32_32x32x16_bf16(a, b, c, 0, 0, 0); }
; DI f32x16 zero16() { f32x16 z; for (int i = 0; i < 16; ++i) z[i] = 0.f; return z; }
; template <int MASK, bool NEAR, int PASS>
; DI void flash_tile(Flash& st, const bf16x8 (&qf)[4], const char* kbuf, const char* vbuf, int pos0, int qpos, bool on,
;                    const float* lut, float bfar, float* imp_row, float rinv) {
;     ...
;     for (int ks = 0; ks < 4; ++ks) {
;         const int ka = r * 128 + (((2 * ks + h) ^ ((r >> 1) & 7)) << 4);
;         const bf16x8 a0 = *(const bf16x8*)(kbuf + ka);
;         const bf16x8 a1 = *(const bf16x8*)(kbuf + 4096 + ka);
;         s[0] = mfma32(a0, qf[ks], s[0]);
;         s[1] = mfma32(a1, qf[ks], s[1]);
;     }
;     constexpr float c1 = 0.125f * LOG2E;
;     float alpha = 1.f;
;     float rs = 0.f;
;     if (!NEAR) {
;         const float bc = MASK == 2 ? 0.f : bfar;
;         float mref;
;         if (PASS != 2) {
;             float mr = s[0][0];
; #pragma unroll
;             for (int i = 1; i < 16; ++i) mr = fmaxf(mr, s[0][i]);
; #pragma unroll
;             for (int i = 0; i < 16; ++i) mr = fmaxf(mr, s[1][i]);
;             float mx = on ? mr * c1 + bc : -1e30f;
;             mx = fmaxf(mx, __shfl_xor(mx, 32));
;             const float mnew = fmaxf(st.m, mx);
;             alpha = fexp2(st.m - mnew);
;             st.m = mnew;
;             mref = mnew;
;         } else mref = st.m;
;         float bm = on ? bc - mref : -1e30f;
;         if (PASS == 2) bm = on ? bm + __log2f(rinv) : -1e30f;
; #pragma unroll
;         for (int tt = 0; tt < 2; ++tt)
; #pragma unroll
;             for (int i = 0; i < 16; ++i) { const float pv = fexp2(s[tt][i] * c1 + bm); s[tt][i] = pv; rs += pv; }
;     ...
;     if (PASS != 2) {
;         rs += __shfl_xor(rs, 32);
;         st.l = st.l * alpha + rs;
;     }
;     f32x16 ia = zero16();
;     if (PASS != 1) {
;         if (PASS == 0) {
; #pragma unroll
;             for (int i = 0; i < 16; ++i) { st.o0[i] *= alpha; st.o1[i] *= alpha; }
;         }
.LBB0_1133:
	s_andn2_saveexec_b64 s[0:1], s[0:1]
	s_cbranch_execz .LBB0_1126
	s_waitcnt lgkmcnt(7)
	v_mfma_f32_32x32x16_bf16 v[52:67], v[36:39], v[94:97], 0
	s_waitcnt lgkmcnt(5)
	v_mfma_f32_32x32x16_bf16 v[52:67], v[150:153], v[98:101], v[52:67]
	v_mfma_f32_32x32x16_bf16 v[36:51], v[138:141], v[94:97], 0
	s_waitcnt lgkmcnt(3)
	v_mfma_f32_32x32x16_bf16 v[52:67], v[146:149], v[102:105], v[52:67]
	v_mfma_f32_32x32x16_bf16 v[36:51], v[134:137], v[98:101], v[36:51]
	s_waitcnt lgkmcnt(1)
	v_mfma_f32_32x32x16_bf16 v[52:67], v[142:145], v[106:109], v[52:67]
	v_mfma_f32_32x32x16_bf16 v[36:51], v[130:133], v[102:105], v[36:51]
	s_nop 10
	v_max_f32_e32 v134, v53, v53
	v_max_f32_e32 v135, v52, v52
	v_max_f32_e32 v134, v135, v134
	v_max3_f32 v130, v134, v54, v55
	v_max3_f32 v130, v130, v56, v57
	v_max3_f32 v130, v130, v58, v59
	v_max3_f32 v130, v130, v60, v61
	s_waitcnt lgkmcnt(0)
	v_mfma_f32_32x32x16_bf16 v[36:51], v[126:129], v[106:109], v[36:51]
	v_max3_f32 v130, v130, v62, v63
	v_max3_f32 v130, v130, v64, v65
	v_max3_f32 v130, v130, v66, v67
	s_nop 8
	v_max3_f32 v126, v130, v36, v37
	v_max3_f32 v126, v126, v38, v39
	v_max3_f32 v126, v126, v40, v41
	v_max3_f32 v126, v126, v42, v43
	v_max3_f32 v126, v126, v44, v45
	v_max3_f32 v126, v126, v46, v47
	v_max3_f32 v126, v126, v48, v49
	v_max3_f32 v126, v126, v50, v51
	v_fmamk_f32 v126, v126, 0x3e38aa3b, v224
	v_cndmask_b32_e64 v126, v215, v126, s[8:9]
	v_mov_b32_e32 v127, v126
	s_nop 1
	v_permlane32_swap_b32_e32 v126, v127
	v_max3_f32 v126, v171, v126, v127
	s_mov_b32 s99, 0x41000000
	v_sub_f32_e32 v127, v126, v171
	v_cmp_lt_f32_e64 s[100:101], s99, v127
	v_cndmask_b32_e64 v126, v171, v126, s[100:101]
	v_sub_f32_e32 v128, v224, v126
	v_cndmask_b32_e64 v128, v215, v128, s[8:9]
	v_fmamk_f32 v52, v52, 0x3e38aa3b, v128
	v_exp_f32_e32 v129, v52
	v_fmamk_f32 v52, v53, 0x3e38aa3b, v128
	v_exp_f32_e32 v53, v52
	v_fmamk_f32 v52, v54, 0x3e38aa3b, v128
	v_exp_f32_e32 v54, v52
	v_fmamk_f32 v52, v55, 0x3e38aa3b, v128
	v_exp_f32_e32 v55, v52
	v_fmamk_f32 v52, v56, 0x3e38aa3b, v128
	v_exp_f32_e32 v56, v52
	v_fmamk_f32 v52, v57, 0x3e38aa3b, v128
	v_exp_f32_e32 v57, v52
	v_fmamk_f32 v52, v58, 0x3e38aa3b, v128
	v_exp_f32_e32 v58, v52
	v_fmamk_f32 v52, v59, 0x3e38aa3b, v128
	v_exp_f32_e32 v59, v52
	v_fmamk_f32 v52, v60, 0x3e38aa3b, v128
	v_exp_f32_e32 v60, v52
	v_fmamk_f32 v52, v61, 0x3e38aa3b, v128
	v_exp_f32_e32 v61, v52
	v_fmamk_f32 v52, v62, 0x3e38aa3b, v128
	v_exp_f32_e32 v62, v52
	v_fmamk_f32 v52, v63, 0x3e38aa3b, v128
	v_exp_f32_e32 v63, v52
	v_fmamk_f32 v52, v64, 0x3e38aa3b, v128
	v_exp_f32_e32 v64, v52
	v_fmamk_f32 v52, v65, 0x3e38aa3b, v128
	v_exp_f32_e32 v65, v52
	v_fmamk_f32 v52, v66, 0x3e38aa3b, v128
	v_fmamk_f32 v66, v67, 0x3e38aa3b, v128
	v_exp_f32_e32 v67, v52
	v_add_f32_e32 v52, 0, v129
	v_add_f32_e32 v52, v53, v52
	v_add_f32_e32 v52, v54, v52
	v_add_f32_e32 v52, v55, v52
	v_add_f32_e32 v52, v56, v52
	v_add_f32_e32 v52, v57, v52
	v_add_f32_e32 v52, v58, v52
	v_add_f32_e32 v52, v59, v52
	v_add_f32_e32 v52, v60, v52
	v_add_f32_e32 v52, v61, v52
	v_add_f32_e32 v52, v62, v52
	v_add_f32_e32 v52, v63, v52
	v_exp_f32_e32 v66, v66
	v_fmamk_f32 v36, v36, 0x3e38aa3b, v128
	v_add_f32_e32 v52, v64, v52
	v_exp_f32_e32 v130, v36
	v_fmamk_f32 v36, v37, 0x3e38aa3b, v128
	v_add_f32_e32 v52, v65, v52
	v_exp_f32_e32 v131, v36
	v_fmamk_f32 v36, v38, 0x3e38aa3b, v128
	v_add_f32_e32 v52, v67, v52
	v_exp_f32_e32 v132, v36
	v_fmamk_f32 v36, v39, 0x3e38aa3b, v128
	v_add_f32_e32 v52, v66, v52
	v_exp_f32_e32 v133, v36
	v_fmamk_f32 v37, v40, 0x3e38aa3b, v128
	v_add_f32_e32 v36, v130, v52
	v_exp_f32_e32 v134, v37
	v_fmamk_f32 v37, v41, 0x3e38aa3b, v128
	v_add_f32_e32 v36, v131, v36
	v_exp_f32_e32 v135, v37
	v_fmamk_f32 v37, v42, 0x3e38aa3b, v128
	v_add_f32_e32 v36, v132, v36
	v_exp_f32_e32 v136, v37
	v_fmamk_f32 v37, v43, 0x3e38aa3b, v128
	v_add_f32_e32 v36, v133, v36
	v_exp_f32_e32 v137, v37
	v_fmamk_f32 v37, v44, 0x3e38aa3b, v128
	v_add_f32_e32 v36, v134, v36
	v_exp_f32_e32 v138, v37
	v_fmamk_f32 v37, v45, 0x3e38aa3b, v128
	v_add_f32_e32 v36, v135, v36
	v_exp_f32_e32 v139, v37
	v_fmamk_f32 v37, v46, 0x3e38aa3b, v128
	v_add_f32_e32 v36, v136, v36
	v_exp_f32_e32 v140, v37
	v_add_f32_e32 v36, v137, v36
	v_add_f32_e32 v36, v138, v36
	v_sub_f32_e32 v127, v171, v126
	v_add_f32_e32 v36, v139, v36
	v_exp_f32_e32 v52, v127
	v_add_f32_e32 v127, v140, v36
	v_fmamk_f32 v36, v47, 0x3e38aa3b, v128
	v_exp_f32_e32 v141, v36
	ds_read_b64_tr_b16 v[36:37], v2 offset:8192
	ds_read_b64_tr_b16 v[38:39], v2 offset:9216
	ds_read_b64_tr_b16 v[46:47], v2 offset:9280
	ds_read_b64_tr_b16 v[44:45], v2 offset:8256
	v_cvt_pk_bf16_f32 v43, v58, v59
	v_cvt_pk_bf16_f32 v42, v56, v57
	v_cvt_pk_bf16_f32 v41, v54, v55
	v_cvt_pk_bf16_f32 v40, v129, v53
	s_cmp_eq_u64 s[100:101], 0
	s_cbranch_scc1 .Llz_gatB
	v_pk_mul_f32 v[34:35], v[34:35], v[52:53] op_sel_hi:[1,0]
	v_pk_mul_f32 v[32:33], v[32:33], v[52:53] op_sel_hi:[1,0]
	v_pk_mul_f32 v[30:31], v[30:31], v[52:53] op_sel_hi:[1,0]
	v_pk_mul_f32 v[28:29], v[28:29], v[52:53] op_sel_hi:[1,0]
	v_pk_mul_f32 v[26:27], v[26:27], v[52:53] op_sel_hi:[1,0]
	v_pk_mul_f32 v[24:25], v[24:25], v[52:53] op_sel_hi:[1,0]
	v_pk_mul_f32 v[22:23], v[22:23], v[52:53] op_sel_hi:[1,0]
	v_pk_mul_f32 v[20:21], v[20:21], v[52:53] op_sel_hi:[1,0]
	v_pk_mul_f32 v[18:19], v[18:19], v[52:53] op_sel_hi:[1,0]
	v_pk_mul_f32 v[16:17], v[16:17], v[52:53] op_sel_hi:[1,0]
	v_pk_mul_f32 v[14:15], v[14:15], v[52:53] op_sel_hi:[1,0]
	v_pk_mul_f32 v[12:13], v[12:13], v[52:53] op_sel_hi:[1,0]
	v_pk_mul_f32 v[10:11], v[10:11], v[52:53] op_sel_hi:[1,0]
	v_pk_mul_f32 v[8:9], v[8:9], v[52:53] op_sel_hi:[1,0]
	v_pk_mul_f32 v[6:7], v[6:7], v[52:53] op_sel_hi:[1,0]
	v_pk_mul_f32 v[4:5], v[4:5], v[52:53] op_sel_hi:[1,0]
	s_nop 1
; DI f32x16 mfma32(bf16x8 a, bf16x8 b, f32x16 c) { return __builtin_amdgcn_mfma_f32_32x32x16_bf16(a, b, c, 0, 0, 0); }
; DI int opaque(int v) { asm volatile("" : "+v"(v)); return v; }
; template <int MASK, bool NEAR, int PASS>
; DI void flash_tile(Flash& st, const bf16x8 (&qf)[4], const char* kbuf, const char* vbuf, int pos0, int qpos, bool on,
;                    const float* lut, float bfar, float* imp_row, float rinv) {
;     ...
;     if (PASS != 2) {
;         rs += __shfl_xor(rs, 32);
;         st.l = st.l * alpha + rs;
;     }
;     ...
;         const int G = lane >> 4, i16 = lane & 15, q = i16 >> 2, pp = i16 & 3;
;         const char* vb = vbuf + (4 * (G >> 1) + q) * 128 + (16 * (G & 1) + 4 * pp) * 2;
; #pragma unroll
;         for (int tt = 0; tt < 2; ++tt)
; #pragma unroll
;             for (int ss = 0; ss < 2; ++ss) {
;                 f32x4 pa = {s[tt][8 * ss], s[tt][8 * ss + 1], s[tt][8 * ss + 2], s[tt][8 * ss + 3]};
;                 f32x4 pb2 = {s[tt][8 * ss + 4], s[tt][8 * ss + 5], s[tt][8 * ss + 6], s[tt][8 * ss + 7]};
;                 const bf16x8 pfrag = cvt8(pa, pb2);
;                 const char* vk = vb + (32 * tt + 16 * ss) * 128;
;                 if (PASS == 2) {
;                     const int d = opaque((lane & 31) - h) - (8 * tt + 4 * ss);
;                     const unsigned one2 = 0x3F803F80u, oneh = 0x3F800000u;
;                     const uint4 ov = {d == 0 ? one2 : 0u, d == 0 ? one2 : (d == 1 ? oneh : 0u), d == 2 ? one2 : 0u, d == 2 ? one2 : (d == 3 ? oneh : 0u)};
;                     ia = mfma32(__builtin_bit_cast(bf16x8, ov), pfrag, ia);
;                 }
;                 {
;                     const s16x4 lo = tr_read(vk), hi = tr_read(vk + 8 * 128);
;                     const bf16x8 va = __builtin_shufflevector(lo, hi, 0, 1, 2, 3, 4, 5, 6, 7);
;                     st.o0 = mfma32(va, pfrag, st.o0);
;                 }
;                 {
;                     const s16x4 lo = tr_read(vk + 64), hi = tr_read(vk + 8 * 128 + 64);
;                     const bf16x8 va = __builtin_shufflevector(lo, hi, 0, 1, 2, 3, 4, 5, 6, 7);
;                     st.o1 = mfma32(va, pfrag, st.o1);
;                 }
;             }
.Llz_gatB:
	s_waitcnt lgkmcnt(2)
	v_mfma_f32_32x32x16_bf16 v[20:35], v[36:39], v[40:43], v[20:35]
	ds_read_b64_tr_b16 v[36:37], v2 offset:10240
	ds_read_b64_tr_b16 v[38:39], v2 offset:11264
	v_fmamk_f32 v50, v50, 0x3e38aa3b, v128
	v_exp_f32_e32 v50, v50
	v_add_f32_e32 v53, v141, v127
	v_mov_b32_e32 v171, v126
	s_waitcnt lgkmcnt(2)
	v_mfma_f32_32x32x16_bf16 v[4:19], v[44:47], v[40:43], v[4:19]
	ds_read_b64_tr_b16 v[46:47], v2 offset:11328
	ds_read_b64_tr_b16 v[44:45], v2 offset:10304
	v_cvt_pk_bf16_f32 v43, v67, v66
	v_cvt_pk_bf16_f32 v42, v64, v65
	v_cvt_pk_bf16_f32 v41, v62, v63
	v_cvt_pk_bf16_f32 v40, v60, v61
	s_waitcnt lgkmcnt(2)
	s_nop 0
	v_mfma_f32_32x32x16_bf16 v[20:35], v[36:39], v[40:43], v[20:35]
	v_fmamk_f32 v36, v48, 0x3e38aa3b, v128
	v_exp_f32_e32 v48, v36
	v_fmamk_f32 v36, v49, 0x3e38aa3b, v128
	v_exp_f32_e32 v49, v36
	ds_read_b64_tr_b16 v[36:37], v2 offset:12288
	ds_read_b64_tr_b16 v[38:39], v2 offset:13312
	v_fmac_f32_e32 v128, 0x3e38aa3b, v51
	v_exp_f32_e32 v51, v128
	s_waitcnt lgkmcnt(2)
	v_mfma_f32_32x32x16_bf16 v[4:19], v[44:47], v[40:43], v[4:19]
	ds_read_b64_tr_b16 v[46:47], v2 offset:13376
	ds_read_b64_tr_b16 v[44:45], v2 offset:12352
	v_cvt_pk_bf16_f32 v43, v136, v137
	v_cvt_pk_bf16_f32 v42, v134, v135
	v_cvt_pk_bf16_f32 v41, v132, v133
	v_cvt_pk_bf16_f32 v40, v130, v131
	s_waitcnt lgkmcnt(2)
	s_nop 0
	v_mfma_f32_32x32x16_bf16 v[20:35], v[36:39], v[40:43], v[20:35]
	v_add_f32_e32 v36, v48, v53
	v_add_f32_e32 v36, v49, v36
	v_add_f32_e32 v53, v50, v36
	ds_read_b64_tr_b16 v[36:37], v2 offset:14336
	ds_read_b64_tr_b16 v[38:39], v2 offset:15360
	v_add_f32_e32 v53, v51, v53
	s_waitcnt lgkmcnt(2)
	v_mfma_f32_32x32x16_bf16 v[4:19], v[44:47], v[40:43], v[4:19]
	ds_read_b64_tr_b16 v[46:47], v2 offset:15424
	ds_read_b64_tr_b16 v[44:45], v2 offset:14400
	v_cvt_pk_bf16_f32 v43, v50, v51
	v_cvt_pk_bf16_f32 v42, v48, v49
	v_cvt_pk_bf16_f32 v41, v140, v141
	v_cvt_pk_bf16_f32 v40, v138, v139
	v_mov_b32_e32 v2, v53
	s_nop 1
	v_permlane32_swap_b32_e32 v53, v2
	v_add_f32_e32 v2, v53, v2
	s_waitcnt lgkmcnt(0)
	v_mfma_f32_32x32x16_bf16 v[20:35], v[36:39], v[40:43], v[20:35]
	v_fmac_f32_e32 v2, v170, v52
	v_mov_b32_e32 v170, v2
	v_mfma_f32_32x32x16_bf16 v[4:19], v[44:47], v[40:43], v[4:19]
	s_branch .LBB0_1126

; DI float fexp2(float x) { return __builtin_amdgcn_exp2f(x); }
; DI f32x16 mfma32(bf16x8 a, bf16x8 b, f32x16 c) { return __builtin_amdgcn_mfma_f32_32x32x16_bf16(a, b, c, 0, 0, 0); }
; DI f32x16 zero16() { f32x16 z; for (int i = 0; i < 16; ++i) z[i] = 0.f; return z; }
; template <int MASK, bool NEAR, int PASS>
; DI void flash_tile(Flash& st, const bf16x8 (&qf)[4], const char* kbuf, const char* vbuf, int pos0, int qpos, bool on,
;                    const float* lut, float bfar, float* imp_row, float rinv) {
;     ...
;     for (int ks = 0; ks < 4; ++ks) {
;         const int ka = r * 128 + (((2 * ks + h) ^ ((r >> 1) & 7)) << 4);
;         const bf16x8 a0 = *(const bf16x8*)(kbuf + ka);
;         const bf16x8 a1 = *(const bf16x8*)(kbuf + 4096 + ka);
;         s[0] = mfma32(a0, qf[ks], s[0]);
;         s[1] = mfma32(a1, qf[ks], s[1]);
;     }
;     constexpr float c1 = 0.125f * LOG2E;
;     float alpha = 1.f;
;     float rs = 0.f;
;     if (!NEAR) {
;         const float bc = MASK == 2 ? 0.f : bfar;
;         float mref;
;         if (PASS != 2) {
;             float mr = s[0][0];
; #pragma unroll
;             for (int i = 1; i < 16; ++i) mr = fmaxf(mr, s[0][i]);
; #pragma unroll
;             for (int i = 0; i < 16; ++i) mr = fmaxf(mr, s[1][i]);
;             float mx = on ? mr * c1 + bc : -1e30f;
;             mx = fmaxf(mx, __shfl_xor(mx, 32));
;             const float mnew = fmaxf(st.m, mx);
;             alpha = fexp2(st.m - mnew);
;             st.m = mnew;
;             mref = mnew;
;         } else mref = st.m;
;         float bm = on ? bc - mref : -1e30f;
;         if (PASS == 2) bm = on ? bm + __log2f(rinv) : -1e30f;
; #pragma unroll
;         for (int tt = 0; tt < 2; ++tt)
; #pragma unroll
;             for (int i = 0; i < 16; ++i) { const float pv = fexp2(s[tt][i] * c1 + bm); s[tt][i] = pv; rs += pv; }
;     ...
;     if (PASS != 2) {
;         rs += __shfl_xor(rs, 32);
;         st.l = st.l * alpha + rs;
;     }
;     f32x16 ia = zero16();
;     if (PASS != 1) {
;         if (PASS == 0) {
; #pragma unroll
;             for (int i = 0; i < 16; ++i) { st.o0[i] *= alpha; st.o1[i] *= alpha; }
;         }
.LBB0_1420:
	s_andn2_saveexec_b64 s[0:1], s[0:1]
	s_cbranch_execz .LBB0_1422
	s_waitcnt lgkmcnt(7)
	v_mfma_f32_32x32x16_bf16 v[66:81], v[50:53], v[94:97], 0
	s_waitcnt lgkmcnt(5)
	v_mfma_f32_32x32x16_bf16 v[66:81], v[150:153], v[98:101], v[66:81]
	v_mfma_f32_32x32x16_bf16 v[50:65], v[138:141], v[94:97], 0
	s_waitcnt lgkmcnt(3)
	v_mfma_f32_32x32x16_bf16 v[66:81], v[146:149], v[102:105], v[66:81]
	v_mfma_f32_32x32x16_bf16 v[50:65], v[12:15], v[98:101], v[50:65]
	s_waitcnt lgkmcnt(1)
	v_mfma_f32_32x32x16_bf16 v[66:81], v[142:145], v[106:109], v[66:81]
	v_mfma_f32_32x32x16_bf16 v[50:65], v[8:11], v[102:105], v[50:65]
	s_nop 10
	v_max_f32_e32 v2, v67, v67
	v_max_f32_e32 v12, v66, v66
	v_max_f32_e32 v2, v12, v2
	v_max3_f32 v2, v2, v68, v69
	v_max3_f32 v2, v2, v70, v71
	v_max3_f32 v2, v2, v72, v73
	v_max3_f32 v2, v2, v74, v75
	s_waitcnt lgkmcnt(0)
	v_mfma_f32_32x32x16_bf16 v[50:65], v[4:7], v[106:109], v[50:65]
	v_max3_f32 v2, v2, v76, v77
	v_max3_f32 v2, v2, v78, v79
	v_max3_f32 v2, v2, v80, v81
	s_nop 8
	v_max3_f32 v2, v2, v50, v51
	v_max3_f32 v2, v2, v52, v53
	v_max3_f32 v2, v2, v54, v55
	v_max3_f32 v2, v2, v56, v57
	v_max3_f32 v2, v2, v58, v59
	v_max3_f32 v2, v2, v60, v61
	v_max3_f32 v2, v2, v62, v63
	v_max3_f32 v2, v2, v64, v65
	v_fmamk_f32 v2, v2, 0x3e38aa3b, v225
	v_cndmask_b32_e64 v2, v215, v2, s[8:9]
	v_mov_b32_e32 v4, v2
	s_nop 1
	v_permlane32_swap_b32_e32 v2, v4
	v_max3_f32 v138, v173, v2, v4
	s_mov_b32 s99, 0x41000000
	v_sub_f32_e32 v4, v138, v173
	v_cmp_lt_f32_e64 s[100:101], s99, v4
	v_cndmask_b32_e64 v138, v173, v138, s[100:101]
	v_sub_f32_e32 v4, v225, v138
	v_cndmask_b32_e64 v139, v215, v4, s[8:9]
	v_fmamk_f32 v4, v66, 0x3e38aa3b, v139
	v_exp_f32_e32 v8, v4
	v_fmamk_f32 v4, v67, 0x3e38aa3b, v139
	v_exp_f32_e32 v12, v4
	v_fmamk_f32 v4, v68, 0x3e38aa3b, v139
	v_exp_f32_e32 v9, v4
	v_fmamk_f32 v4, v69, 0x3e38aa3b, v139
	v_exp_f32_e32 v13, v4
	v_fmamk_f32 v4, v70, 0x3e38aa3b, v139
	v_exp_f32_e32 v10, v4
	v_fmamk_f32 v4, v71, 0x3e38aa3b, v139
	v_exp_f32_e32 v14, v4
	v_fmamk_f32 v4, v72, 0x3e38aa3b, v139
	v_exp_f32_e32 v11, v4
	v_fmamk_f32 v4, v73, 0x3e38aa3b, v139
	v_exp_f32_e32 v15, v4
	v_fmamk_f32 v4, v74, 0x3e38aa3b, v139
	v_exp_f32_e32 v66, v4
	v_fmamk_f32 v4, v75, 0x3e38aa3b, v139
	v_exp_f32_e32 v67, v4
	v_fmamk_f32 v4, v76, 0x3e38aa3b, v139
	v_exp_f32_e32 v68, v4
	v_fmamk_f32 v4, v77, 0x3e38aa3b, v139
	v_exp_f32_e32 v69, v4
	v_fmamk_f32 v4, v78, 0x3e38aa3b, v139
	v_exp_f32_e32 v70, v4
	v_fmamk_f32 v4, v79, 0x3e38aa3b, v139
	v_exp_f32_e32 v71, v4
	v_fmamk_f32 v4, v80, 0x3e38aa3b, v139
	v_exp_f32_e32 v72, v4
	v_add_f32_e32 v4, 0, v8
	v_add_f32_e32 v4, v12, v4
	v_add_f32_e32 v4, v9, v4
	v_add_f32_e32 v4, v13, v4
	v_add_f32_e32 v4, v10, v4
	v_add_f32_e32 v4, v14, v4
	v_add_f32_e32 v4, v11, v4
	v_add_f32_e32 v4, v15, v4
	v_add_f32_e32 v4, v66, v4
	v_add_f32_e32 v4, v67, v4
	v_fmamk_f32 v5, v81, 0x3e38aa3b, v139
	v_add_f32_e32 v4, v68, v4
	v_add_f32_e32 v4, v69, v4
	v_exp_f32_e32 v73, v5
	v_fmamk_f32 v5, v50, 0x3e38aa3b, v139
	v_add_f32_e32 v4, v70, v4
	v_exp_f32_e32 v50, v5
	v_fmamk_f32 v5, v51, 0x3e38aa3b, v139
	v_add_f32_e32 v4, v71, v4
	v_exp_f32_e32 v51, v5
	v_fmamk_f32 v5, v52, 0x3e38aa3b, v139
	v_add_f32_e32 v4, v72, v4
	v_exp_f32_e32 v52, v5
	v_fmamk_f32 v5, v53, 0x3e38aa3b, v139
	v_add_f32_e32 v4, v73, v4
	v_exp_f32_e32 v53, v5
	v_fmamk_f32 v5, v54, 0x3e38aa3b, v139
	v_add_f32_e32 v4, v50, v4
	v_exp_f32_e32 v54, v5
	v_fmamk_f32 v5, v55, 0x3e38aa3b, v139
	v_add_f32_e32 v4, v51, v4
	v_exp_f32_e32 v55, v5
	v_fmamk_f32 v5, v56, 0x3e38aa3b, v139
	v_add_f32_e32 v4, v52, v4
	v_exp_f32_e32 v56, v5
	v_fmamk_f32 v5, v57, 0x3e38aa3b, v139
	v_add_f32_e32 v4, v53, v4
	v_exp_f32_e32 v57, v5
	v_fmamk_f32 v5, v58, 0x3e38aa3b, v139
	v_add_f32_e32 v4, v54, v4
	v_exp_f32_e32 v58, v5
	v_fmamk_f32 v5, v59, 0x3e38aa3b, v139
	v_add_f32_e32 v4, v55, v4
	v_exp_f32_e32 v59, v5
	v_fmamk_f32 v5, v60, 0x3e38aa3b, v139
	v_add_f32_e32 v4, v56, v4
	v_exp_f32_e32 v60, v5
	v_add_f32_e32 v4, v57, v4
	v_add_f32_e32 v4, v58, v4
	v_add_f32_e32 v4, v59, v4
	v_sub_f32_e32 v2, v173, v138
	v_add_f32_e32 v74, v60, v4
	v_fmamk_f32 v4, v61, 0x3e38aa3b, v139
	v_exp_f32_e32 v2, v2
	v_exp_f32_e32 v61, v4
	ds_read_b64_tr_b16 v[4:5], v194 offset:8192
	ds_read_b64_tr_b16 v[6:7], v194 offset:9216
	v_cvt_pk_bf16_f32 v11, v11, v15
	v_cvt_pk_bf16_f32 v10, v10, v14
	v_cvt_pk_bf16_f32 v9, v9, v13
	v_cvt_pk_bf16_f32 v8, v8, v12
	ds_read_b64_tr_b16 v[14:15], v194 offset:9280
	ds_read_b64_tr_b16 v[12:13], v194 offset:8256
	s_cmp_eq_u64 s[100:101], 0
	s_cbranch_scc1 .Llz_winA
	v_pk_mul_f32 v[48:49], v[48:49], v[2:3] op_sel_hi:[1,0]
	v_pk_mul_f32 v[46:47], v[46:47], v[2:3] op_sel_hi:[1,0]
	v_pk_mul_f32 v[44:45], v[44:45], v[2:3] op_sel_hi:[1,0]
	v_pk_mul_f32 v[42:43], v[42:43], v[2:3] op_sel_hi:[1,0]
	v_pk_mul_f32 v[40:41], v[40:41], v[2:3] op_sel_hi:[1,0]
	v_pk_mul_f32 v[38:39], v[38:39], v[2:3] op_sel_hi:[1,0]
	v_pk_mul_f32 v[36:37], v[36:37], v[2:3] op_sel_hi:[1,0]
	v_pk_mul_f32 v[34:35], v[34:35], v[2:3] op_sel_hi:[1,0]
	v_pk_mul_f32 v[32:33], v[32:33], v[2:3] op_sel_hi:[1,0]
	v_pk_mul_f32 v[30:31], v[30:31], v[2:3] op_sel_hi:[1,0]
	v_pk_mul_f32 v[28:29], v[28:29], v[2:3] op_sel_hi:[1,0]
	v_pk_mul_f32 v[26:27], v[26:27], v[2:3] op_sel_hi:[1,0]
	v_pk_mul_f32 v[24:25], v[24:25], v[2:3] op_sel_hi:[1,0]
	v_pk_mul_f32 v[22:23], v[22:23], v[2:3] op_sel_hi:[1,0]
	v_pk_mul_f32 v[20:21], v[20:21], v[2:3] op_sel_hi:[1,0]
	v_pk_mul_f32 v[18:19], v[18:19], v[2:3] op_sel_hi:[1,0]
	s_nop 1
; DI f32x16 mfma32(bf16x8 a, bf16x8 b, f32x16 c) { return __builtin_amdgcn_mfma_f32_32x32x16_bf16(a, b, c, 0, 0, 0); }
; DI int opaque(int v) { asm volatile("" : "+v"(v)); return v; }
; template <int MASK, bool NEAR, int PASS>
; DI void flash_tile(Flash& st, const bf16x8 (&qf)[4], const char* kbuf, const char* vbuf, int pos0, int qpos, bool on,
;                    const float* lut, float bfar, float* imp_row, float rinv) {
;     ...
;     if (PASS != 2) {
;         rs += __shfl_xor(rs, 32);
;         st.l = st.l * alpha + rs;
;     }
;     ...
;         const int G = lane >> 4, i16 = lane & 15, q = i16 >> 2, pp = i16 & 3;
;         const char* vb = vbuf + (4 * (G >> 1) + q) * 128 + (16 * (G & 1) + 4 * pp) * 2;
; #pragma unroll
;         for (int tt = 0; tt < 2; ++tt)
; #pragma unroll
;             for (int ss = 0; ss < 2; ++ss) {
;                 f32x4 pa = {s[tt][8 * ss], s[tt][8 * ss + 1], s[tt][8 * ss + 2], s[tt][8 * ss + 3]};
;                 f32x4 pb2 = {s[tt][8 * ss + 4], s[tt][8 * ss + 5], s[tt][8 * ss + 6], s[tt][8 * ss + 7]};
;                 const bf16x8 pfrag = cvt8(pa, pb2);
;                 const char* vk = vb + (32 * tt + 16 * ss) * 128;
;                 if (PASS == 2) {
;                     const int d = opaque((lane & 31) - h) - (8 * tt + 4 * ss);
;                     const unsigned one2 = 0x3F803F80u, oneh = 0x3F800000u;
;                     const uint4 ov = {d == 0 ? one2 : 0u, d == 0 ? one2 : (d == 1 ? oneh : 0u), d == 2 ? one2 : 0u, d == 2 ? one2 : (d == 3 ? oneh : 0u)};
;                     ia = mfma32(__builtin_bit_cast(bf16x8, ov), pfrag, ia);
;                 }
;                 {
;                     const s16x4 lo = tr_read(vk), hi = tr_read(vk + 8 * 128);
;                     const bf16x8 va = __builtin_shufflevector(lo, hi, 0, 1, 2, 3, 4, 5, 6, 7);
;                     st.o0 = mfma32(va, pfrag, st.o0);
;                 }
;                 {
;                     const s16x4 lo = tr_read(vk + 64), hi = tr_read(vk + 8 * 128 + 64);
;                     const bf16x8 va = __builtin_shufflevector(lo, hi, 0, 1, 2, 3, 4, 5, 6, 7);
;                     st.o1 = mfma32(va, pfrag, st.o1);
;                 }
;             }
.Llz_winA:
	s_waitcnt lgkmcnt(2)
	v_mfma_f32_32x32x16_bf16 v[34:49], v[4:7], v[8:11], v[34:49]
	ds_read_b64_tr_b16 v[4:5], v194 offset:10240
	ds_read_b64_tr_b16 v[6:7], v194 offset:11264
	v_fmamk_f32 v64, v64, 0x3e38aa3b, v139
	v_exp_f32_e32 v64, v64
	v_add_f32_e32 v74, v61, v74
	v_mov_b32_e32 v173, v138
	s_waitcnt lgkmcnt(2)
	v_mfma_f32_32x32x16_bf16 v[18:33], v[12:15], v[8:11], v[18:33]
	ds_read_b64_tr_b16 v[14:15], v194 offset:11328
	ds_read_b64_tr_b16 v[12:13], v194 offset:10304
	v_cvt_pk_bf16_f32 v11, v72, v73
	v_cvt_pk_bf16_f32 v10, v70, v71
	v_cvt_pk_bf16_f32 v9, v68, v69
	v_cvt_pk_bf16_f32 v8, v66, v67
	s_waitcnt lgkmcnt(2)
	s_nop 0
	v_mfma_f32_32x32x16_bf16 v[34:49], v[4:7], v[8:11], v[34:49]
	v_fmamk_f32 v4, v62, 0x3e38aa3b, v139
	v_exp_f32_e32 v62, v4
	v_fmamk_f32 v4, v63, 0x3e38aa3b, v139
	v_exp_f32_e32 v63, v4
	ds_read_b64_tr_b16 v[4:5], v194 offset:12288
	ds_read_b64_tr_b16 v[6:7], v194 offset:13312
	v_fmac_f32_e32 v139, 0x3e38aa3b, v65
	s_waitcnt lgkmcnt(2)
	v_mfma_f32_32x32x16_bf16 v[18:33], v[12:15], v[8:11], v[18:33]
	ds_read_b64_tr_b16 v[14:15], v194 offset:13376
	ds_read_b64_tr_b16 v[12:13], v194 offset:12352
	v_cvt_pk_bf16_f32 v11, v56, v57
	v_cvt_pk_bf16_f32 v10, v54, v55
	v_cvt_pk_bf16_f32 v9, v52, v53
	v_cvt_pk_bf16_f32 v8, v50, v51
	v_exp_f32_e32 v51, v139
	s_waitcnt lgkmcnt(2)
	v_mfma_f32_32x32x16_bf16 v[34:49], v[4:7], v[8:11], v[34:49]
	v_add_f32_e32 v4, v62, v74
	v_add_f32_e32 v4, v63, v4
	v_add_f32_e32 v50, v64, v4
	ds_read_b64_tr_b16 v[4:5], v194 offset:14336
	ds_read_b64_tr_b16 v[6:7], v194 offset:15360
	v_add_f32_e32 v50, v51, v50
	s_waitcnt lgkmcnt(2)
	v_mfma_f32_32x32x16_bf16 v[18:33], v[12:15], v[8:11], v[18:33]
	ds_read_b64_tr_b16 v[14:15], v194 offset:15424
	ds_read_b64_tr_b16 v[12:13], v194 offset:14400
	v_cvt_pk_bf16_f32 v11, v64, v51
	v_cvt_pk_bf16_f32 v10, v62, v63
	v_cvt_pk_bf16_f32 v9, v60, v61
	v_cvt_pk_bf16_f32 v8, v58, v59
	s_waitcnt lgkmcnt(2)
	s_nop 0
	v_mfma_f32_32x32x16_bf16 v[34:49], v[4:7], v[8:11], v[34:49]
	v_mov_b32_e32 v4, v50
	s_nop 1
	v_permlane32_swap_b32_e32 v50, v4
	v_add_f32_e32 v4, v50, v4
	s_waitcnt lgkmcnt(0)
	v_fmac_f32_e32 v4, v157, v2
	v_mfma_f32_32x32x16_bf16 v[18:33], v[12:15], v[8:11], v[18:33]
	v_mov_b32_e32 v157, v4

; DI float fexp2(float x) { return __builtin_amdgcn_exp2f(x); }
; DI f32x16 mfma32(bf16x8 a, bf16x8 b, f32x16 c) { return __builtin_amdgcn_mfma_f32_32x32x16_bf16(a, b, c, 0, 0, 0); }
; DI f32x16 zero16() { f32x16 z; for (int i = 0; i < 16; ++i) z[i] = 0.f; return z; }
; template <int MASK, bool NEAR, int PASS>
; DI void flash_tile(Flash& st, const bf16x8 (&qf)[4], const char* kbuf, const char* vbuf, int pos0, int qpos, bool on,
;                    const float* lut, float bfar, float* imp_row, float rinv) {
;     ...
;     for (int ks = 0; ks < 4; ++ks) {
;         const int ka = r * 128 + (((2 * ks + h) ^ ((r >> 1) & 7)) << 4);
;         const bf16x8 a0 = *(const bf16x8*)(kbuf + ka);
;         const bf16x8 a1 = *(const bf16x8*)(kbuf + 4096 + ka);
;         s[0] = mfma32(a0, qf[ks], s[0]);
;         s[1] = mfma32(a1, qf[ks], s[1]);
;     }
;     constexpr float c1 = 0.125f * LOG2E;
;     float alpha = 1.f;
;     float rs = 0.f;
;     if (!NEAR) {
;         const float bc = MASK == 2 ? 0.f : bfar;
;         float mref;
;         if (PASS != 2) {
;             float mr = s[0][0];
; #pragma unroll
;             for (int i = 1; i < 16; ++i) mr = fmaxf(mr, s[0][i]);
; #pragma unroll
;             for (int i = 0; i < 16; ++i) mr = fmaxf(mr, s[1][i]);
;             float mx = on ? mr * c1 + bc : -1e30f;
;             mx = fmaxf(mx, __shfl_xor(mx, 32));
;             const float mnew = fmaxf(st.m, mx);
;             alpha = fexp2(st.m - mnew);
;             st.m = mnew;
;             mref = mnew;
;         } else mref = st.m;
;         float bm = on ? bc - mref : -1e30f;
;         if (PASS == 2) bm = on ? bm + __log2f(rinv) : -1e30f;
; #pragma unroll
;         for (int tt = 0; tt < 2; ++tt)
; #pragma unroll
;             for (int i = 0; i < 16; ++i) { const float pv = fexp2(s[tt][i] * c1 + bm); s[tt][i] = pv; rs += pv; }
;     ...
;     if (PASS != 2) {
;         rs += __shfl_xor(rs, 32);
;         st.l = st.l * alpha + rs;
;     }
;     f32x16 ia = zero16();
;     if (PASS != 1) {
;         if (PASS == 0) {
; #pragma unroll
;             for (int i = 0; i < 16; ++i) { st.o0[i] *= alpha; st.o1[i] *= alpha; }
;         }
.LBB0_1429:
	s_andn2_saveexec_b64 s[0:1], s[0:1]
	s_cbranch_execz .LBB0_1413
	s_waitcnt lgkmcnt(7)
	v_mfma_f32_32x32x16_bf16 v[66:81], v[50:53], v[94:97], 0
	s_waitcnt lgkmcnt(5)
	v_mfma_f32_32x32x16_bf16 v[66:81], v[150:153], v[98:101], v[66:81]
	v_mfma_f32_32x32x16_bf16 v[50:65], v[138:141], v[94:97], 0
	s_waitcnt lgkmcnt(3)
	v_mfma_f32_32x32x16_bf16 v[66:81], v[146:149], v[102:105], v[66:81]
	v_mfma_f32_32x32x16_bf16 v[50:65], v[12:15], v[98:101], v[50:65]
	s_waitcnt lgkmcnt(1)
	v_mfma_f32_32x32x16_bf16 v[66:81], v[142:145], v[106:109], v[66:81]
	v_mfma_f32_32x32x16_bf16 v[50:65], v[8:11], v[102:105], v[50:65]
	s_nop 10
	v_max_f32_e32 v2, v67, v67
	v_max_f32_e32 v12, v66, v66
	v_max_f32_e32 v2, v12, v2
	v_max3_f32 v2, v2, v68, v69
	v_max3_f32 v2, v2, v70, v71
	v_max3_f32 v2, v2, v72, v73
	v_max3_f32 v2, v2, v74, v75
	s_waitcnt lgkmcnt(0)
	v_mfma_f32_32x32x16_bf16 v[50:65], v[4:7], v[106:109], v[50:65]
	v_max3_f32 v2, v2, v76, v77
	v_max3_f32 v2, v2, v78, v79
	v_max3_f32 v2, v2, v80, v81
	s_nop 8
	v_max3_f32 v2, v2, v50, v51
	v_max3_f32 v2, v2, v52, v53
	v_max3_f32 v2, v2, v54, v55
	v_max3_f32 v2, v2, v56, v57
	v_max3_f32 v2, v2, v58, v59
	v_max3_f32 v2, v2, v60, v61
	v_max3_f32 v2, v2, v62, v63
	v_max3_f32 v2, v2, v64, v65
	v_fmamk_f32 v2, v2, 0x3e38aa3b, v225
	v_cndmask_b32_e64 v2, v215, v2, s[8:9]
	v_mov_b32_e32 v4, v2
	s_nop 1
	v_permlane32_swap_b32_e32 v2, v4
	v_max3_f32 v16, v173, v2, v4
	s_mov_b32 s99, 0x41000000
	v_sub_f32_e32 v4, v16, v173
	v_cmp_lt_f32_e64 s[100:101], s99, v4
	v_cndmask_b32_e64 v16, v173, v16, s[100:101]
	v_sub_f32_e32 v4, v225, v16
	v_cndmask_b32_e64 v17, v215, v4, s[8:9]
	v_fmamk_f32 v4, v66, 0x3e38aa3b, v17
	v_exp_f32_e32 v8, v4
	v_fmamk_f32 v4, v67, 0x3e38aa3b, v17
	v_exp_f32_e32 v12, v4
	v_fmamk_f32 v4, v68, 0x3e38aa3b, v17
	v_exp_f32_e32 v9, v4
	v_fmamk_f32 v4, v69, 0x3e38aa3b, v17
	v_exp_f32_e32 v13, v4
	v_fmamk_f32 v4, v70, 0x3e38aa3b, v17
	v_exp_f32_e32 v10, v4
	v_fmamk_f32 v4, v71, 0x3e38aa3b, v17
	v_exp_f32_e32 v14, v4
	v_fmamk_f32 v4, v72, 0x3e38aa3b, v17
	v_exp_f32_e32 v11, v4
	v_fmamk_f32 v4, v73, 0x3e38aa3b, v17
	v_exp_f32_e32 v15, v4
	v_fmamk_f32 v4, v74, 0x3e38aa3b, v17
	v_exp_f32_e32 v66, v4
	v_fmamk_f32 v4, v75, 0x3e38aa3b, v17
	v_exp_f32_e32 v67, v4
	v_fmamk_f32 v4, v76, 0x3e38aa3b, v17
	v_exp_f32_e32 v68, v4
	v_fmamk_f32 v4, v77, 0x3e38aa3b, v17
	v_exp_f32_e32 v69, v4
	v_fmamk_f32 v4, v78, 0x3e38aa3b, v17
	v_exp_f32_e32 v70, v4
	v_fmamk_f32 v4, v79, 0x3e38aa3b, v17
	v_exp_f32_e32 v71, v4
	v_fmamk_f32 v4, v80, 0x3e38aa3b, v17
	v_exp_f32_e32 v72, v4
	v_add_f32_e32 v4, 0, v8
	v_add_f32_e32 v4, v12, v4
	v_add_f32_e32 v4, v9, v4
	v_add_f32_e32 v4, v13, v4
	v_add_f32_e32 v4, v10, v4
	v_add_f32_e32 v4, v14, v4
	v_add_f32_e32 v4, v11, v4
	v_add_f32_e32 v4, v15, v4
	v_add_f32_e32 v4, v66, v4
	v_add_f32_e32 v4, v67, v4
	v_fmamk_f32 v5, v81, 0x3e38aa3b, v17
	v_add_f32_e32 v4, v68, v4
	v_add_f32_e32 v4, v69, v4
	v_exp_f32_e32 v73, v5
	v_fmamk_f32 v5, v50, 0x3e38aa3b, v17
	v_add_f32_e32 v4, v70, v4
	v_exp_f32_e32 v50, v5
	v_fmamk_f32 v5, v51, 0x3e38aa3b, v17
	v_add_f32_e32 v4, v71, v4
	v_exp_f32_e32 v51, v5
	v_fmamk_f32 v5, v52, 0x3e38aa3b, v17
	v_add_f32_e32 v4, v72, v4
	v_exp_f32_e32 v52, v5
	v_fmamk_f32 v5, v53, 0x3e38aa3b, v17
	v_add_f32_e32 v4, v73, v4
	v_exp_f32_e32 v53, v5
	v_fmamk_f32 v5, v54, 0x3e38aa3b, v17
	v_add_f32_e32 v4, v50, v4
	v_exp_f32_e32 v54, v5
	v_fmamk_f32 v5, v55, 0x3e38aa3b, v17
	v_add_f32_e32 v4, v51, v4
	v_exp_f32_e32 v55, v5
	v_fmamk_f32 v5, v56, 0x3e38aa3b, v17
	v_add_f32_e32 v4, v52, v4
	v_exp_f32_e32 v56, v5
	v_fmamk_f32 v5, v57, 0x3e38aa3b, v17
	v_add_f32_e32 v4, v53, v4
	v_exp_f32_e32 v57, v5
	v_fmamk_f32 v5, v58, 0x3e38aa3b, v17
	v_add_f32_e32 v4, v54, v4
	v_exp_f32_e32 v58, v5
	v_fmamk_f32 v5, v59, 0x3e38aa3b, v17
	v_add_f32_e32 v4, v55, v4
	v_exp_f32_e32 v59, v5
	v_fmamk_f32 v5, v60, 0x3e38aa3b, v17
	v_add_f32_e32 v4, v56, v4
	v_exp_f32_e32 v60, v5
	v_add_f32_e32 v4, v57, v4
	v_add_f32_e32 v4, v58, v4
	v_add_f32_e32 v4, v59, v4
	v_sub_f32_e32 v2, v173, v16
	v_add_f32_e32 v74, v60, v4
	v_fmamk_f32 v4, v61, 0x3e38aa3b, v17
	v_exp_f32_e32 v2, v2
	v_exp_f32_e32 v61, v4
	ds_read_b64_tr_b16 v[4:5], v194 offset:24576
	ds_read_b64_tr_b16 v[6:7], v194 offset:25600
	v_cvt_pk_bf16_f32 v11, v11, v15
	v_cvt_pk_bf16_f32 v10, v10, v14
	v_cvt_pk_bf16_f32 v9, v9, v13
	v_cvt_pk_bf16_f32 v8, v8, v12
	ds_read_b64_tr_b16 v[14:15], v194 offset:25664
	ds_read_b64_tr_b16 v[12:13], v194 offset:24640
	s_cmp_eq_u64 s[100:101], 0
	s_cbranch_scc1 .Llz_winB
	v_pk_mul_f32 v[48:49], v[48:49], v[2:3] op_sel_hi:[1,0]
	v_pk_mul_f32 v[46:47], v[46:47], v[2:3] op_sel_hi:[1,0]
	v_pk_mul_f32 v[44:45], v[44:45], v[2:3] op_sel_hi:[1,0]
	v_pk_mul_f32 v[42:43], v[42:43], v[2:3] op_sel_hi:[1,0]
	v_pk_mul_f32 v[40:41], v[40:41], v[2:3] op_sel_hi:[1,0]
	v_pk_mul_f32 v[38:39], v[38:39], v[2:3] op_sel_hi:[1,0]
	v_pk_mul_f32 v[36:37], v[36:37], v[2:3] op_sel_hi:[1,0]
	v_pk_mul_f32 v[34:35], v[34:35], v[2:3] op_sel_hi:[1,0]
	v_pk_mul_f32 v[32:33], v[32:33], v[2:3] op_sel_hi:[1,0]
	v_pk_mul_f32 v[30:31], v[30:31], v[2:3] op_sel_hi:[1,0]
	v_pk_mul_f32 v[28:29], v[28:29], v[2:3] op_sel_hi:[1,0]
	v_pk_mul_f32 v[26:27], v[26:27], v[2:3] op_sel_hi:[1,0]
	v_pk_mul_f32 v[24:25], v[24:25], v[2:3] op_sel_hi:[1,0]
	v_pk_mul_f32 v[22:23], v[22:23], v[2:3] op_sel_hi:[1,0]
	v_pk_mul_f32 v[20:21], v[20:21], v[2:3] op_sel_hi:[1,0]
	v_pk_mul_f32 v[18:19], v[18:19], v[2:3] op_sel_hi:[1,0]
	s_nop 1
; DI f32x16 mfma32(bf16x8 a, bf16x8 b, f32x16 c) { return __builtin_amdgcn_mfma_f32_32x32x16_bf16(a, b, c, 0, 0, 0); }
; DI int opaque(int v) { asm volatile("" : "+v"(v)); return v; }
; template <int MASK, bool NEAR, int PASS>
; DI void flash_tile(Flash& st, const bf16x8 (&qf)[4], const char* kbuf, const char* vbuf, int pos0, int qpos, bool on,
;                    const float* lut, float bfar, float* imp_row, float rinv) {
;     ...
;     if (PASS != 2) {
;         rs += __shfl_xor(rs, 32);
;         st.l = st.l * alpha + rs;
;     }
;     ...
;         const int G = lane >> 4, i16 = lane & 15, q = i16 >> 2, pp = i16 & 3;
;         const char* vb = vbuf + (4 * (G >> 1) + q) * 128 + (16 * (G & 1) + 4 * pp) * 2;
; #pragma unroll
;         for (int tt = 0; tt < 2; ++tt)
; #pragma unroll
;             for (int ss = 0; ss < 2; ++ss) {
;                 f32x4 pa = {s[tt][8 * ss], s[tt][8 * ss + 1], s[tt][8 * ss + 2], s[tt][8 * ss + 3]};
;                 f32x4 pb2 = {s[tt][8 * ss + 4], s[tt][8 * ss + 5], s[tt][8 * ss + 6], s[tt][8 * ss + 7]};
;                 const bf16x8 pfrag = cvt8(pa, pb2);
;                 const char* vk = vb + (32 * tt + 16 * ss) * 128;
;                 if (PASS == 2) {
;                     const int d = opaque((lane & 31) - h) - (8 * tt + 4 * ss);
;                     const unsigned one2 = 0x3F803F80u, oneh = 0x3F800000u;
;                     const uint4 ov = {d == 0 ? one2 : 0u, d == 0 ? one2 : (d == 1 ? oneh : 0u), d == 2 ? one2 : 0u, d == 2 ? one2 : (d == 3 ? oneh : 0u)};
;                     ia = mfma32(__builtin_bit_cast(bf16x8, ov), pfrag, ia);
;                 }
;                 {
;                     const s16x4 lo = tr_read(vk), hi = tr_read(vk + 8 * 128);
;                     const bf16x8 va = __builtin_shufflevector(lo, hi, 0, 1, 2, 3, 4, 5, 6, 7);
;                     st.o0 = mfma32(va, pfrag, st.o0);
;                 }
;                 {
;                     const s16x4 lo = tr_read(vk + 64), hi = tr_read(vk + 8 * 128 + 64);
;                     const bf16x8 va = __builtin_shufflevector(lo, hi, 0, 1, 2, 3, 4, 5, 6, 7);
;                     st.o1 = mfma32(va, pfrag, st.o1);
;                 }
;             }
.Llz_winB:
	s_waitcnt lgkmcnt(2)
	v_mfma_f32_32x32x16_bf16 v[34:49], v[4:7], v[8:11], v[34:49]
	ds_read_b64_tr_b16 v[4:5], v194 offset:26624
	ds_read_b64_tr_b16 v[6:7], v194 offset:27648
	v_fmamk_f32 v64, v64, 0x3e38aa3b, v17
	v_exp_f32_e32 v64, v64
	v_add_f32_e32 v74, v61, v74
	v_mov_b32_e32 v173, v16
	s_waitcnt lgkmcnt(2)
	v_mfma_f32_32x32x16_bf16 v[18:33], v[12:15], v[8:11], v[18:33]
	ds_read_b64_tr_b16 v[14:15], v194 offset:27712
	ds_read_b64_tr_b16 v[12:13], v194 offset:26688
	v_cvt_pk_bf16_f32 v11, v72, v73
	v_cvt_pk_bf16_f32 v10, v70, v71
	v_cvt_pk_bf16_f32 v9, v68, v69
	v_cvt_pk_bf16_f32 v8, v66, v67
	s_waitcnt lgkmcnt(2)
	s_nop 0
	v_mfma_f32_32x32x16_bf16 v[34:49], v[4:7], v[8:11], v[34:49]
	v_fmamk_f32 v4, v62, 0x3e38aa3b, v17
	v_exp_f32_e32 v62, v4
	v_fmamk_f32 v4, v63, 0x3e38aa3b, v17
	v_exp_f32_e32 v63, v4
	ds_read_b64_tr_b16 v[4:5], v194 offset:28672
	ds_read_b64_tr_b16 v[6:7], v194 offset:29696
	v_fmac_f32_e32 v17, 0x3e38aa3b, v65
	v_exp_f32_e32 v17, v17
	s_waitcnt lgkmcnt(2)
	v_mfma_f32_32x32x16_bf16 v[18:33], v[12:15], v[8:11], v[18:33]
	ds_read_b64_tr_b16 v[14:15], v194 offset:29760
	ds_read_b64_tr_b16 v[12:13], v194 offset:28736
	v_cvt_pk_bf16_f32 v11, v56, v57
	v_cvt_pk_bf16_f32 v10, v54, v55
	v_cvt_pk_bf16_f32 v9, v52, v53
	v_cvt_pk_bf16_f32 v8, v50, v51
	s_waitcnt lgkmcnt(2)
	s_nop 0
	v_mfma_f32_32x32x16_bf16 v[34:49], v[4:7], v[8:11], v[34:49]
	v_add_f32_e32 v4, v62, v74
	v_add_f32_e32 v4, v63, v4
	v_add_f32_e32 v50, v64, v4
	ds_read_b64_tr_b16 v[4:5], v194 offset:30720
	ds_read_b64_tr_b16 v[6:7], v194 offset:31744
	v_add_f32_e32 v50, v17, v50
	s_waitcnt lgkmcnt(2)
	v_mfma_f32_32x32x16_bf16 v[18:33], v[12:15], v[8:11], v[18:33]
	ds_read_b64_tr_b16 v[14:15], v194 offset:31808
	ds_read_b64_tr_b16 v[12:13], v194 offset:30784
	v_cvt_pk_bf16_f32 v11, v64, v17
	v_cvt_pk_bf16_f32 v10, v62, v63
	v_cvt_pk_bf16_f32 v9, v60, v61
	v_cvt_pk_bf16_f32 v8, v58, v59
	s_waitcnt lgkmcnt(2)
	s_nop 0
	v_mfma_f32_32x32x16_bf16 v[34:49], v[4:7], v[8:11], v[34:49]
	v_mov_b32_e32 v4, v50
	s_nop 1
	v_permlane32_swap_b32_e32 v50, v4
	v_add_f32_e32 v4, v50, v4
	s_waitcnt lgkmcnt(0)
	v_fmac_f32_e32 v4, v157, v2
	v_mfma_f32_32x32x16_bf16 v[18:33], v[12:15], v[8:11], v[18:33]
	v_mov_b32_e32 v157, v4
	s_branch .LBB0_1413

; template <int MASK, bool NEAR, int PASS>
; DI void flash_tile(Flash& st, const bf16x8 (&qf)[4], const char* kbuf, const char* vbuf, int pos0, int qpos, bool on,
;                    const float* lut, float bfar, float* imp_row, float rinv) {
;     ...
;     for (int ks = 0; ks < 4; ++ks) {
;         const int ka = r * 128 + (((2 * ks + h) ^ ((r >> 1) & 7)) << 4);
;         const bf16x8 a0 = *(const bf16x8*)(kbuf + ka);
;         const bf16x8 a1 = *(const bf16x8*)(kbuf + 4096 + ka);
;         s[0] = mfma32(a0, qf[ks], s[0]);
;         s[1] = mfma32(a1, qf[ks], s[1]);
;     }
;     constexpr float c1 = 0.125f * LOG2E;
;     float alpha = 1.f;
;     float rs = 0.f;
;     if (!NEAR) {
;         const float bc = MASK == 2 ? 0.f : bfar;
;         float mref;
;         if (PASS != 2) {
;             float mr = s[0][0];
; #pragma unroll
;             for (int i = 1; i < 16; ++i) mr = fmaxf(mr, s[0][i]);
; #pragma unroll
;             for (int i = 0; i < 16; ++i) mr = fmaxf(mr, s[1][i]);
;             float mx = on ? mr * c1 + bc : -1e30f;
;             mx = fmaxf(mx, __shfl_xor(mx, 32));
;             const float mnew = fmaxf(st.m, mx);
;             alpha = fexp2(st.m - mnew);
;             st.m = mnew;
;             mref = mnew;
;         } else mref = st.m;
;         float bm = on ? bc - mref : -1e30f;
;         if (PASS == 2) bm = on ? bm + __log2f(rinv) : -1e30f;
; #pragma unroll
;         for (int tt = 0; tt < 2; ++tt)
; #pragma unroll
;             for (int i = 0; i < 16; ++i) { const float pv = fexp2(s[tt][i] * c1 + bm); s[tt][i] = pv; rs += pv; }
;     ...
;     if (PASS != 2) {
;         rs += __shfl_xor(rs, 32);
;         st.l = st.l * alpha + rs;
;     }
;     f32x16 ia = zero16();
;     if (PASS != 1) {
;         if (PASS == 0) {
; #pragma unroll
;             for (int i = 0; i < 16; ++i) { st.o0[i] *= alpha; st.o1[i] *= alpha; }
;         }
; template <int MASK, int PASS>
; DI void run_tiles_b(Flash& st, const bf16x8 (&qf)[4], const BSrc& src, const int* list, int n, char* kvbuf, int qpos,
;                     int qmin_w, int qmax_w, const OnFn onfn, const float* lut, float bfar, float* imp_row, float rinv) {
;     ...
;     for (int i = 0; i < n; i += 2) {
;         {
;             tileb_store(RA, kvbuf, kvbuf + 8192);
;             __syncthreads();
;             const int pos0 = list[i];
;             if (i + 2 < n) tileb_issue(RA, src, list[i + 2]);
.LBB0_1522:
	s_cmp_eq_u64 exec, 0
	s_cbranch_scc1 .LBB0_1528
	v_add_u32_e32 v2, 0, v190
	ds_read_b128 v[50:53], v2
	ds_read_b128 v[130:133], v2 offset:4096
	v_add_u32_e32 v2, 0, v191
	ds_read_b128 v[142:145], v2
	ds_read_b128 v[12:15], v2 offset:4096
	v_add_u32_e32 v2, 0, v192
	ds_read_b128 v[138:141], v2
	ds_read_b128 v[8:11], v2 offset:4096
	v_add_u32_e32 v2, 0, v193
	ds_read_b128 v[134:137], v2
	ds_read_b128 v[4:7], v2 offset:4096
	s_waitcnt lgkmcnt(8)
	v_add_u32_e32 v2, 0xb0, v66
	v_cmp_le_i32_e32 vcc, v2, v158
	s_and_saveexec_b64 s[2:3], vcc
	s_xor_b64 s[2:3], exec, s[2:3]
	s_cbranch_execz .LBB0_1525
	s_waitcnt lgkmcnt(7)
	v_mfma_f32_32x32x16_bf16 v[66:81], v[50:53], v[82:85], 0
	s_waitcnt lgkmcnt(5)
	v_mfma_f32_32x32x16_bf16 v[66:81], v[142:145], v[86:89], v[66:81]
	v_mfma_f32_32x32x16_bf16 v[50:65], v[130:133], v[82:85], 0
	s_waitcnt lgkmcnt(3)
	v_mfma_f32_32x32x16_bf16 v[66:81], v[138:141], v[90:93], v[66:81]
	v_mfma_f32_32x32x16_bf16 v[50:65], v[12:15], v[86:89], v[50:65]
	s_waitcnt lgkmcnt(1)
	v_mfma_f32_32x32x16_bf16 v[66:81], v[134:137], v[94:97], v[66:81]
	v_mfma_f32_32x32x16_bf16 v[50:65], v[8:11], v[90:93], v[50:65]
	s_nop 10
	v_max_f32_e32 v2, v67, v67
	v_max_f32_e32 v12, v66, v66
	v_max_f32_e32 v2, v12, v2
	v_max3_f32 v2, v2, v68, v69
	v_max3_f32 v2, v2, v70, v71
	v_max3_f32 v2, v2, v72, v73
	v_max3_f32 v2, v2, v74, v75
	s_waitcnt lgkmcnt(0)
	v_mfma_f32_32x32x16_bf16 v[50:65], v[4:7], v[94:97], v[50:65]
	v_max3_f32 v2, v2, v76, v77
	v_max3_f32 v2, v2, v78, v79
	v_max3_f32 v2, v2, v80, v81
	v_and_b32_e32 v5, 64, v188
	v_xor_b32_e32 v4, 32, v188
	v_add_u32_e32 v5, 64, v5
	v_cmp_lt_i32_e32 vcc, v4, v5
	s_nop 4
	v_max3_f32 v2, v2, v50, v51
	v_max3_f32 v2, v2, v52, v53
	v_max3_f32 v2, v2, v54, v55
	v_max3_f32 v2, v2, v56, v57
	v_max3_f32 v2, v2, v58, v59
	v_max3_f32 v2, v2, v60, v61
	v_max3_f32 v2, v2, v62, v63
	v_max3_f32 v2, v2, v64, v65
	v_cndmask_b32_e32 v4, v188, v4, vcc
	v_fmamk_f32 v2, v2, 0x3e38aa3b, v162
	v_lshlrev_b32_e32 v130, 2, v4
	v_mov_b32_e32 v4, v2
	s_nop 1
	v_permlane32_swap_b32_e32 v2, v4
	v_max3_f32 v131, v165, v2, v4
	s_mov_b32 s99, 0x41000000
	v_sub_f32_e32 v4, v131, v165
	v_cmp_lt_f32_e64 s[100:101], s99, v4
	v_cndmask_b32_e64 v131, v165, v131, s[100:101]
	v_sub_f32_e32 v132, v162, v131
	v_fmamk_f32 v2, v66, 0x3e38aa3b, v132
	v_exp_f32_e32 v8, v2
	v_fmamk_f32 v5, v67, 0x3e38aa3b, v132
	v_exp_f32_e32 v12, v5
	v_fmamk_f32 v5, v68, 0x3e38aa3b, v132
	v_exp_f32_e32 v9, v5
	v_fmamk_f32 v5, v69, 0x3e38aa3b, v132
	v_exp_f32_e32 v13, v5
	v_fmamk_f32 v5, v70, 0x3e38aa3b, v132
	v_add_f32_e32 v4, 0, v8
	v_exp_f32_e32 v10, v5
	v_fmamk_f32 v5, v71, 0x3e38aa3b, v132
	v_exp_f32_e32 v14, v5
	v_fmamk_f32 v5, v72, 0x3e38aa3b, v132
	v_add_f32_e32 v4, v12, v4
	v_exp_f32_e32 v11, v5
	v_fmamk_f32 v5, v73, 0x3e38aa3b, v132
	v_add_f32_e32 v4, v9, v4
	v_exp_f32_e32 v15, v5
	v_fmamk_f32 v5, v74, 0x3e38aa3b, v132
	v_add_f32_e32 v4, v13, v4
	v_exp_f32_e32 v66, v5
	v_fmamk_f32 v5, v75, 0x3e38aa3b, v132
	v_add_f32_e32 v4, v10, v4
	v_exp_f32_e32 v67, v5
	v_fmamk_f32 v5, v76, 0x3e38aa3b, v132
	v_add_f32_e32 v4, v14, v4
	v_exp_f32_e32 v68, v5
	v_fmamk_f32 v5, v77, 0x3e38aa3b, v132
	v_add_f32_e32 v4, v11, v4
	v_exp_f32_e32 v69, v5
	v_fmamk_f32 v5, v78, 0x3e38aa3b, v132
	v_add_f32_e32 v4, v15, v4
	v_add_f32_e32 v4, v66, v4
	v_exp_f32_e32 v70, v5
	v_fmamk_f32 v5, v79, 0x3e38aa3b, v132
	v_add_f32_e32 v4, v67, v4
	v_exp_f32_e32 v71, v5
	v_fmamk_f32 v5, v80, 0x3e38aa3b, v132
	v_add_f32_e32 v4, v68, v4
	v_exp_f32_e32 v72, v5
	v_fmamk_f32 v5, v81, 0x3e38aa3b, v132
	v_add_f32_e32 v4, v69, v4
	v_exp_f32_e32 v73, v5
	v_fmamk_f32 v5, v50, 0x3e38aa3b, v132
	v_add_f32_e32 v4, v70, v4
	v_exp_f32_e32 v50, v5
	v_fmamk_f32 v5, v51, 0x3e38aa3b, v132
	v_add_f32_e32 v4, v71, v4
	v_exp_f32_e32 v51, v5
	v_fmamk_f32 v5, v52, 0x3e38aa3b, v132
	v_add_f32_e32 v4, v72, v4
	v_exp_f32_e32 v52, v5
	v_fmamk_f32 v5, v53, 0x3e38aa3b, v132
	v_add_f32_e32 v4, v73, v4
	v_exp_f32_e32 v53, v5
	v_fmamk_f32 v5, v54, 0x3e38aa3b, v132
	v_add_f32_e32 v4, v50, v4
	v_exp_f32_e32 v54, v5
	v_fmamk_f32 v5, v55, 0x3e38aa3b, v132
	v_add_f32_e32 v4, v51, v4
	v_exp_f32_e32 v55, v5
	v_fmamk_f32 v5, v56, 0x3e38aa3b, v132
	v_add_f32_e32 v4, v52, v4
	v_exp_f32_e32 v56, v5
	v_fmamk_f32 v5, v57, 0x3e38aa3b, v132
	v_add_f32_e32 v4, v53, v4
	v_exp_f32_e32 v57, v5
	v_fmamk_f32 v5, v58, 0x3e38aa3b, v132
	v_add_f32_e32 v4, v54, v4
	v_exp_f32_e32 v58, v5
	v_fmamk_f32 v5, v59, 0x3e38aa3b, v132
	v_add_f32_e32 v4, v55, v4
	v_exp_f32_e32 v59, v5
	v_fmamk_f32 v5, v60, 0x3e38aa3b, v132
	v_add_f32_e32 v4, v56, v4
	v_exp_f32_e32 v60, v5
	v_add_f32_e32 v4, v57, v4
	v_add_f32_e32 v4, v58, v4
	v_add_f32_e32 v4, v59, v4
	v_sub_f32_e32 v2, v165, v131
	v_add_f32_e32 v74, v60, v4
	v_fmamk_f32 v4, v61, 0x3e38aa3b, v132
	v_exp_f32_e32 v2, v2
	v_exp_f32_e32 v61, v4
	ds_read_b64_tr_b16 v[4:5], v194 offset:8192
	ds_read_b64_tr_b16 v[6:7], v194 offset:9216
	v_cvt_pk_bf16_f32 v11, v11, v15
	v_cvt_pk_bf16_f32 v10, v10, v14
	v_cvt_pk_bf16_f32 v9, v9, v13
	v_cvt_pk_bf16_f32 v8, v8, v12
	ds_read_b64_tr_b16 v[14:15], v194 offset:9280
	ds_read_b64_tr_b16 v[12:13], v194 offset:8256
	s_cmp_eq_u64 s[100:101], 0
	s_cbranch_scc1 .Llz_ownA
	v_pk_mul_f32 v[48:49], v[48:49], v[2:3] op_sel_hi:[1,0]
	v_pk_mul_f32 v[46:47], v[46:47], v[2:3] op_sel_hi:[1,0]
	v_pk_mul_f32 v[44:45], v[44:45], v[2:3] op_sel_hi:[1,0]
	v_pk_mul_f32 v[42:43], v[42:43], v[2:3] op_sel_hi:[1,0]
	v_pk_mul_f32 v[40:41], v[40:41], v[2:3] op_sel_hi:[1,0]
	v_pk_mul_f32 v[38:39], v[38:39], v[2:3] op_sel_hi:[1,0]
	v_pk_mul_f32 v[36:37], v[36:37], v[2:3] op_sel_hi:[1,0]
	v_pk_mul_f32 v[34:35], v[34:35], v[2:3] op_sel_hi:[1,0]
	v_pk_mul_f32 v[32:33], v[32:33], v[2:3] op_sel_hi:[1,0]
	v_pk_mul_f32 v[30:31], v[30:31], v[2:3] op_sel_hi:[1,0]
	v_pk_mul_f32 v[28:29], v[28:29], v[2:3] op_sel_hi:[1,0]
	v_pk_mul_f32 v[26:27], v[26:27], v[2:3] op_sel_hi:[1,0]
	v_pk_mul_f32 v[24:25], v[24:25], v[2:3] op_sel_hi:[1,0]
	v_pk_mul_f32 v[22:23], v[22:23], v[2:3] op_sel_hi:[1,0]
	v_pk_mul_f32 v[20:21], v[20:21], v[2:3] op_sel_hi:[1,0]
	v_pk_mul_f32 v[18:19], v[18:19], v[2:3] op_sel_hi:[1,0]
	s_nop 1
; DI f32x16 mfma32(bf16x8 a, bf16x8 b, f32x16 c) { return __builtin_amdgcn_mfma_f32_32x32x16_bf16(a, b, c, 0, 0, 0); }
; DI int opaque(int v) { asm volatile("" : "+v"(v)); return v; }
; template <int MASK, bool NEAR, int PASS>
; DI void flash_tile(Flash& st, const bf16x8 (&qf)[4], const char* kbuf, const char* vbuf, int pos0, int qpos, bool on,
;                    const float* lut, float bfar, float* imp_row, float rinv) {
;     ...
;     if (PASS != 2) {
;         rs += __shfl_xor(rs, 32);
;         st.l = st.l * alpha + rs;
;     }
;     ...
;         const int G = lane >> 4, i16 = lane & 15, q = i16 >> 2, pp = i16 & 3;
;         const char* vb = vbuf + (4 * (G >> 1) + q) * 128 + (16 * (G & 1) + 4 * pp) * 2;
; #pragma unroll
;         for (int tt = 0; tt < 2; ++tt)
; #pragma unroll
;             for (int ss = 0; ss < 2; ++ss) {
;                 f32x4 pa = {s[tt][8 * ss], s[tt][8 * ss + 1], s[tt][8 * ss + 2], s[tt][8 * ss + 3]};
;                 f32x4 pb2 = {s[tt][8 * ss + 4], s[tt][8 * ss + 5], s[tt][8 * ss + 6], s[tt][8 * ss + 7]};
;                 const bf16x8 pfrag = cvt8(pa, pb2);
;                 const char* vk = vb + (32 * tt + 16 * ss) * 128;
;                 if (PASS == 2) {
;                     const int d = opaque((lane & 31) - h) - (8 * tt + 4 * ss);
;                     const unsigned one2 = 0x3F803F80u, oneh = 0x3F800000u;
;                     const uint4 ov = {d == 0 ? one2 : 0u, d == 0 ? one2 : (d == 1 ? oneh : 0u), d == 2 ? one2 : 0u, d == 2 ? one2 : (d == 3 ? oneh : 0u)};
;                     ia = mfma32(__builtin_bit_cast(bf16x8, ov), pfrag, ia);
;                 }
;                 {
;                     const s16x4 lo = tr_read(vk), hi = tr_read(vk + 8 * 128);
;                     const bf16x8 va = __builtin_shufflevector(lo, hi, 0, 1, 2, 3, 4, 5, 6, 7);
;                     st.o0 = mfma32(va, pfrag, st.o0);
;                 }
;                 {
;                     const s16x4 lo = tr_read(vk + 64), hi = tr_read(vk + 8 * 128 + 64);
;                     const bf16x8 va = __builtin_shufflevector(lo, hi, 0, 1, 2, 3, 4, 5, 6, 7);
;                     st.o1 = mfma32(va, pfrag, st.o1);
;                 }
;             }
.Llz_ownA:
	s_waitcnt lgkmcnt(2)
	v_mfma_f32_32x32x16_bf16 v[34:49], v[4:7], v[8:11], v[34:49]
	ds_read_b64_tr_b16 v[4:5], v194 offset:10240
	ds_read_b64_tr_b16 v[6:7], v194 offset:11264
	v_fmamk_f32 v64, v64, 0x3e38aa3b, v132
	v_exp_f32_e32 v64, v64
	v_add_f32_e32 v74, v61, v74
	v_mov_b32_e32 v165, v131
	s_waitcnt lgkmcnt(2)
	v_mfma_f32_32x32x16_bf16 v[18:33], v[12:15], v[8:11], v[18:33]
	ds_read_b64_tr_b16 v[14:15], v194 offset:11328
	ds_read_b64_tr_b16 v[12:13], v194 offset:10304
	v_cvt_pk_bf16_f32 v11, v72, v73
	v_cvt_pk_bf16_f32 v10, v70, v71
	v_cvt_pk_bf16_f32 v9, v68, v69
	v_cvt_pk_bf16_f32 v8, v66, v67
	s_waitcnt lgkmcnt(2)
	s_nop 0
	v_mfma_f32_32x32x16_bf16 v[34:49], v[4:7], v[8:11], v[34:49]
	v_fmamk_f32 v4, v62, 0x3e38aa3b, v132
	v_exp_f32_e32 v62, v4
	v_fmamk_f32 v4, v63, 0x3e38aa3b, v132
	v_exp_f32_e32 v63, v4
	ds_read_b64_tr_b16 v[4:5], v194 offset:12288
	ds_read_b64_tr_b16 v[6:7], v194 offset:13312
	v_fmac_f32_e32 v132, 0x3e38aa3b, v65
	s_waitcnt lgkmcnt(2)
	v_mfma_f32_32x32x16_bf16 v[18:33], v[12:15], v[8:11], v[18:33]
	ds_read_b64_tr_b16 v[14:15], v194 offset:13376
	ds_read_b64_tr_b16 v[12:13], v194 offset:12352
	v_cvt_pk_bf16_f32 v11, v56, v57
	v_cvt_pk_bf16_f32 v10, v54, v55
	v_cvt_pk_bf16_f32 v9, v52, v53
	v_cvt_pk_bf16_f32 v8, v50, v51
	v_exp_f32_e32 v51, v132
	s_waitcnt lgkmcnt(2)
	v_mfma_f32_32x32x16_bf16 v[34:49], v[4:7], v[8:11], v[34:49]
	v_add_f32_e32 v4, v62, v74
	v_add_f32_e32 v4, v63, v4
	v_add_f32_e32 v50, v64, v4
	ds_read_b64_tr_b16 v[4:5], v194 offset:14336
	ds_read_b64_tr_b16 v[6:7], v194 offset:15360
	v_add_f32_e32 v50, v51, v50
	s_waitcnt lgkmcnt(2)
	v_mfma_f32_32x32x16_bf16 v[18:33], v[12:15], v[8:11], v[18:33]
	ds_read_b64_tr_b16 v[14:15], v194 offset:15424
	ds_read_b64_tr_b16 v[12:13], v194 offset:14400
	v_cvt_pk_bf16_f32 v11, v64, v51
	v_cvt_pk_bf16_f32 v10, v62, v63
	v_cvt_pk_bf16_f32 v9, v60, v61
	v_cvt_pk_bf16_f32 v8, v58, v59
	s_waitcnt lgkmcnt(2)
	s_nop 0
	v_mfma_f32_32x32x16_bf16 v[34:49], v[4:7], v[8:11], v[34:49]
	v_mov_b32_e32 v4, v50
	s_nop 1
	v_permlane32_swap_b32_e32 v50, v4
	v_add_f32_e32 v4, v50, v4
	s_waitcnt lgkmcnt(0)
	v_fmac_f32_e32 v4, v160, v2
	v_mfma_f32_32x32x16_bf16 v[18:33], v[12:15], v[8:11], v[18:33]
	v_mov_b32_e32 v160, v4

; template <int MASK, bool NEAR, int PASS>
; DI void flash_tile(Flash& st, const bf16x8 (&qf)[4], const char* kbuf, const char* vbuf, int pos0, int qpos, bool on,
;                    const float* lut, float bfar, float* imp_row, float rinv) {
;     ...
;     for (int ks = 0; ks < 4; ++ks) {
;         const int ka = r * 128 + (((2 * ks + h) ^ ((r >> 1) & 7)) << 4);
;         const bf16x8 a0 = *(const bf16x8*)(kbuf + ka);
;         const bf16x8 a1 = *(const bf16x8*)(kbuf + 4096 + ka);
;         s[0] = mfma32(a0, qf[ks], s[0]);
;         s[1] = mfma32(a1, qf[ks], s[1]);
;     }
;     constexpr float c1 = 0.125f * LOG2E;
;     float alpha = 1.f;
;     float rs = 0.f;
;     if (!NEAR) {
;         const float bc = MASK == 2 ? 0.f : bfar;
;         float mref;
;         if (PASS != 2) {
;             float mr = s[0][0];
; #pragma unroll
;             for (int i = 1; i < 16; ++i) mr = fmaxf(mr, s[0][i]);
; #pragma unroll
;             for (int i = 0; i < 16; ++i) mr = fmaxf(mr, s[1][i]);
;             float mx = on ? mr * c1 + bc : -1e30f;
;             mx = fmaxf(mx, __shfl_xor(mx, 32));
;             const float mnew = fmaxf(st.m, mx);
;             alpha = fexp2(st.m - mnew);
;             st.m = mnew;
;             mref = mnew;
;         } else mref = st.m;
;         float bm = on ? bc - mref : -1e30f;
;         if (PASS == 2) bm = on ? bm + __log2f(rinv) : -1e30f;
; #pragma unroll
;         for (int tt = 0; tt < 2; ++tt)
; #pragma unroll
;             for (int i = 0; i < 16; ++i) { const float pv = fexp2(s[tt][i] * c1 + bm); s[tt][i] = pv; rs += pv; }
;     ...
;     if (PASS != 2) {
;         rs += __shfl_xor(rs, 32);
;         st.l = st.l * alpha + rs;
;     }
;     f32x16 ia = zero16();
;     if (PASS != 1) {
;         if (PASS == 0) {
; #pragma unroll
;             for (int i = 0; i < 16; ++i) { st.o0[i] *= alpha; st.o1[i] *= alpha; }
;         }
; template <int MASK, int PASS>
; DI void run_tiles_b(Flash& st, const bf16x8 (&qf)[4], const BSrc& src, const int* list, int n, char* kvbuf, int qpos,
;                     int qmin_w, int qmax_w, const OnFn onfn, const float* lut, float bfar, float* imp_row, float rinv) {
;     ...
;     for (int i = 0; i < n; i += 2) {
;         {
;             tileb_store(RA, kvbuf, kvbuf + 8192);
;             __syncthreads();
;             const int pos0 = list[i];
;             if (i + 2 < n) tileb_issue(RA, src, list[i + 2]);
.LBB0_1531:
	s_cmp_eq_u64 exec, 0
	s_cbranch_scc1 .LBB0_1537
	v_add_u32_e32 v2, 0, v190
	ds_read_b128 v[50:53], v2 offset:16384
	ds_read_b128 v[130:133], v2 offset:20480
	v_add_u32_e32 v2, 0, v191
	ds_read_b128 v[142:145], v2 offset:16384
	ds_read_b128 v[12:15], v2 offset:20480
	v_add_u32_e32 v2, 0, v192
	ds_read_b128 v[138:141], v2 offset:16384
	ds_read_b128 v[8:11], v2 offset:20480
	v_add_u32_e32 v2, 0, v193
	ds_read_b128 v[134:137], v2 offset:16384
	ds_read_b128 v[4:7], v2 offset:20480
	s_waitcnt lgkmcnt(8)
	v_add_u32_e32 v2, 0xb0, v16
	v_cmp_le_i32_e32 vcc, v2, v158
	s_and_saveexec_b64 s[2:3], vcc
	s_xor_b64 s[2:3], exec, s[2:3]
	s_cbranch_execz .LBB0_1534
	s_waitcnt lgkmcnt(7)
	v_mfma_f32_32x32x16_bf16 v[66:81], v[50:53], v[82:85], 0
	s_waitcnt lgkmcnt(5)
	v_mfma_f32_32x32x16_bf16 v[66:81], v[142:145], v[86:89], v[66:81]
	v_mfma_f32_32x32x16_bf16 v[50:65], v[130:133], v[82:85], 0
	s_waitcnt lgkmcnt(3)
	v_mfma_f32_32x32x16_bf16 v[66:81], v[138:141], v[90:93], v[66:81]
	v_mfma_f32_32x32x16_bf16 v[50:65], v[12:15], v[86:89], v[50:65]
	s_waitcnt lgkmcnt(1)
	v_mfma_f32_32x32x16_bf16 v[66:81], v[134:137], v[94:97], v[66:81]
	v_mfma_f32_32x32x16_bf16 v[50:65], v[8:11], v[90:93], v[50:65]
	s_nop 10
	v_max_f32_e32 v2, v67, v67
	v_max_f32_e32 v12, v66, v66
	v_max_f32_e32 v2, v12, v2
	v_max3_f32 v2, v2, v68, v69
	v_max3_f32 v2, v2, v70, v71
	v_max3_f32 v2, v2, v72, v73
	v_max3_f32 v2, v2, v74, v75
	s_waitcnt lgkmcnt(0)
	v_mfma_f32_32x32x16_bf16 v[50:65], v[4:7], v[94:97], v[50:65]
	v_max3_f32 v2, v2, v76, v77
	v_max3_f32 v2, v2, v78, v79
	v_max3_f32 v2, v2, v80, v81
	v_and_b32_e32 v5, 64, v188
	v_xor_b32_e32 v4, 32, v188
	v_add_u32_e32 v5, 64, v5
	v_cmp_lt_i32_e32 vcc, v4, v5
	s_nop 4
	v_max3_f32 v2, v2, v50, v51
	v_max3_f32 v2, v2, v52, v53
	v_max3_f32 v2, v2, v54, v55
	v_max3_f32 v2, v2, v56, v57
	v_max3_f32 v2, v2, v58, v59
	v_max3_f32 v2, v2, v60, v61
	v_max3_f32 v2, v2, v62, v63
	v_max3_f32 v2, v2, v64, v65
	v_cndmask_b32_e32 v4, v188, v4, vcc
	v_fmamk_f32 v2, v2, 0x3e38aa3b, v162
	v_lshlrev_b32_e32 v16, 2, v4
	v_mov_b32_e32 v4, v2
	s_nop 1
	v_permlane32_swap_b32_e32 v2, v4
	v_max3_f32 v17, v165, v2, v4
	s_mov_b32 s99, 0x41000000
	v_sub_f32_e32 v4, v17, v165
	v_cmp_lt_f32_e64 s[100:101], s99, v4
	v_cndmask_b32_e64 v17, v165, v17, s[100:101]
	v_sub_f32_e32 v130, v162, v17
	v_fmamk_f32 v2, v66, 0x3e38aa3b, v130
	v_exp_f32_e32 v8, v2
	v_fmamk_f32 v5, v67, 0x3e38aa3b, v130
	v_exp_f32_e32 v12, v5
	v_fmamk_f32 v5, v68, 0x3e38aa3b, v130
	v_exp_f32_e32 v9, v5
	v_fmamk_f32 v5, v69, 0x3e38aa3b, v130
	v_exp_f32_e32 v13, v5
	v_fmamk_f32 v5, v70, 0x3e38aa3b, v130
	v_add_f32_e32 v4, 0, v8
	v_exp_f32_e32 v10, v5
	v_fmamk_f32 v5, v71, 0x3e38aa3b, v130
	v_exp_f32_e32 v14, v5
	v_fmamk_f32 v5, v72, 0x3e38aa3b, v130
	v_add_f32_e32 v4, v12, v4
	v_exp_f32_e32 v11, v5
	v_fmamk_f32 v5, v73, 0x3e38aa3b, v130
	v_add_f32_e32 v4, v9, v4
	v_exp_f32_e32 v15, v5
	v_fmamk_f32 v5, v74, 0x3e38aa3b, v130
	v_add_f32_e32 v4, v13, v4
	v_exp_f32_e32 v66, v5
	v_fmamk_f32 v5, v75, 0x3e38aa3b, v130
	v_add_f32_e32 v4, v10, v4
	v_exp_f32_e32 v67, v5
	v_fmamk_f32 v5, v76, 0x3e38aa3b, v130
	v_add_f32_e32 v4, v14, v4
	v_exp_f32_e32 v68, v5
	v_fmamk_f32 v5, v77, 0x3e38aa3b, v130
	v_add_f32_e32 v4, v11, v4
	v_exp_f32_e32 v69, v5
	v_fmamk_f32 v5, v78, 0x3e38aa3b, v130
	v_add_f32_e32 v4, v15, v4
	v_add_f32_e32 v4, v66, v4
	v_exp_f32_e32 v70, v5
	v_fmamk_f32 v5, v79, 0x3e38aa3b, v130
	v_add_f32_e32 v4, v67, v4
	v_exp_f32_e32 v71, v5
	v_fmamk_f32 v5, v80, 0x3e38aa3b, v130
	v_add_f32_e32 v4, v68, v4
	v_exp_f32_e32 v72, v5
	v_fmamk_f32 v5, v81, 0x3e38aa3b, v130
	v_add_f32_e32 v4, v69, v4
	v_exp_f32_e32 v73, v5
	v_fmamk_f32 v5, v50, 0x3e38aa3b, v130
	v_add_f32_e32 v4, v70, v4
	v_exp_f32_e32 v50, v5
	v_fmamk_f32 v5, v51, 0x3e38aa3b, v130
	v_add_f32_e32 v4, v71, v4
	v_exp_f32_e32 v51, v5
	v_fmamk_f32 v5, v52, 0x3e38aa3b, v130
	v_add_f32_e32 v4, v72, v4
	v_exp_f32_e32 v52, v5
	v_fmamk_f32 v5, v53, 0x3e38aa3b, v130
	v_add_f32_e32 v4, v73, v4
	v_exp_f32_e32 v53, v5
	v_fmamk_f32 v5, v54, 0x3e38aa3b, v130
	v_add_f32_e32 v4, v50, v4
	v_exp_f32_e32 v54, v5
	v_fmamk_f32 v5, v55, 0x3e38aa3b, v130
	v_add_f32_e32 v4, v51, v4
	v_exp_f32_e32 v55, v5
	v_fmamk_f32 v5, v56, 0x3e38aa3b, v130
	v_add_f32_e32 v4, v52, v4
	v_exp_f32_e32 v56, v5
	v_fmamk_f32 v5, v57, 0x3e38aa3b, v130
	v_add_f32_e32 v4, v53, v4
	v_exp_f32_e32 v57, v5
	v_fmamk_f32 v5, v58, 0x3e38aa3b, v130
	v_add_f32_e32 v4, v54, v4
	v_exp_f32_e32 v58, v5
	v_fmamk_f32 v5, v59, 0x3e38aa3b, v130
	v_add_f32_e32 v4, v55, v4
	v_exp_f32_e32 v59, v5
	v_fmamk_f32 v5, v60, 0x3e38aa3b, v130
	v_add_f32_e32 v4, v56, v4
	v_exp_f32_e32 v60, v5
	v_add_f32_e32 v4, v57, v4
	v_add_f32_e32 v4, v58, v4
	v_add_f32_e32 v4, v59, v4
	v_sub_f32_e32 v2, v165, v17
	v_add_f32_e32 v74, v60, v4
	v_fmamk_f32 v4, v61, 0x3e38aa3b, v130
	v_exp_f32_e32 v2, v2
	v_exp_f32_e32 v61, v4
	ds_read_b64_tr_b16 v[4:5], v194 offset:24576
	ds_read_b64_tr_b16 v[6:7], v194 offset:25600
	v_cvt_pk_bf16_f32 v11, v11, v15
	v_cvt_pk_bf16_f32 v10, v10, v14
	v_cvt_pk_bf16_f32 v9, v9, v13
	v_cvt_pk_bf16_f32 v8, v8, v12
	ds_read_b64_tr_b16 v[14:15], v194 offset:25664
	ds_read_b64_tr_b16 v[12:13], v194 offset:24640
	s_cmp_eq_u64 s[100:101], 0
	s_cbranch_scc1 .Llz_ownB
	v_pk_mul_f32 v[48:49], v[48:49], v[2:3] op_sel_hi:[1,0]
	v_pk_mul_f32 v[46:47], v[46:47], v[2:3] op_sel_hi:[1,0]
	v_pk_mul_f32 v[44:45], v[44:45], v[2:3] op_sel_hi:[1,0]
	v_pk_mul_f32 v[42:43], v[42:43], v[2:3] op_sel_hi:[1,0]
	v_pk_mul_f32 v[40:41], v[40:41], v[2:3] op_sel_hi:[1,0]
	v_pk_mul_f32 v[38:39], v[38:39], v[2:3] op_sel_hi:[1,0]
	v_pk_mul_f32 v[36:37], v[36:37], v[2:3] op_sel_hi:[1,0]
	v_pk_mul_f32 v[34:35], v[34:35], v[2:3] op_sel_hi:[1,0]
	v_pk_mul_f32 v[32:33], v[32:33], v[2:3] op_sel_hi:[1,0]
	v_pk_mul_f32 v[30:31], v[30:31], v[2:3] op_sel_hi:[1,0]
	v_pk_mul_f32 v[28:29], v[28:29], v[2:3] op_sel_hi:[1,0]
	v_pk_mul_f32 v[26:27], v[26:27], v[2:3] op_sel_hi:[1,0]
	v_pk_mul_f32 v[24:25], v[24:25], v[2:3] op_sel_hi:[1,0]
	v_pk_mul_f32 v[22:23], v[22:23], v[2:3] op_sel_hi:[1,0]
	v_pk_mul_f32 v[20:21], v[20:21], v[2:3] op_sel_hi:[1,0]
	v_pk_mul_f32 v[18:19], v[18:19], v[2:3] op_sel_hi:[1,0]
	s_nop 1
; DI f32x16 mfma32(bf16x8 a, bf16x8 b, f32x16 c) { return __builtin_amdgcn_mfma_f32_32x32x16_bf16(a, b, c, 0, 0, 0); }
; DI int opaque(int v) { asm volatile("" : "+v"(v)); return v; }
; template <int MASK, bool NEAR, int PASS>
; DI void flash_tile(Flash& st, const bf16x8 (&qf)[4], const char* kbuf, const char* vbuf, int pos0, int qpos, bool on,
;                    const float* lut, float bfar, float* imp_row, float rinv) {
;     ...
;     if (PASS != 2) {
;         rs += __shfl_xor(rs, 32);
;         st.l = st.l * alpha + rs;
;     }
;     ...
;         const int G = lane >> 4, i16 = lane & 15, q = i16 >> 2, pp = i16 & 3;
;         const char* vb = vbuf + (4 * (G >> 1) + q) * 128 + (16 * (G & 1) + 4 * pp) * 2;
; #pragma unroll
;         for (int tt = 0; tt < 2; ++tt)
; #pragma unroll
;             for (int ss = 0; ss < 2; ++ss) {
;                 f32x4 pa = {s[tt][8 * ss], s[tt][8 * ss + 1], s[tt][8 * ss + 2], s[tt][8 * ss + 3]};
;                 f32x4 pb2 = {s[tt][8 * ss + 4], s[tt][8 * ss + 5], s[tt][8 * ss + 6], s[tt][8 * ss + 7]};
;                 const bf16x8 pfrag = cvt8(pa, pb2);
;                 const char* vk = vb + (32 * tt + 16 * ss) * 128;
;                 if (PASS == 2) {
;                     const int d = opaque((lane & 31) - h) - (8 * tt + 4 * ss);
;                     const unsigned one2 = 0x3F803F80u, oneh = 0x3F800000u;
;                     const uint4 ov = {d == 0 ? one2 : 0u, d == 0 ? one2 : (d == 1 ? oneh : 0u), d == 2 ? one2 : 0u, d == 2 ? one2 : (d == 3 ? oneh : 0u)};
;                     ia = mfma32(__builtin_bit_cast(bf16x8, ov), pfrag, ia);
;                 }
;                 {
;                     const s16x4 lo = tr_read(vk), hi = tr_read(vk + 8 * 128);
;                     const bf16x8 va = __builtin_shufflevector(lo, hi, 0, 1, 2, 3, 4, 5, 6, 7);
;                     st.o0 = mfma32(va, pfrag, st.o0);
;                 }
;                 {
;                     const s16x4 lo = tr_read(vk + 64), hi = tr_read(vk + 8 * 128 + 64);
;                     const bf16x8 va = __builtin_shufflevector(lo, hi, 0, 1, 2, 3, 4, 5, 6, 7);
;                     st.o1 = mfma32(va, pfrag, st.o1);
;                 }
;             }
.Llz_ownB:
	s_waitcnt lgkmcnt(2)
	v_mfma_f32_32x32x16_bf16 v[34:49], v[4:7], v[8:11], v[34:49]
	ds_read_b64_tr_b16 v[4:5], v194 offset:26624
	ds_read_b64_tr_b16 v[6:7], v194 offset:27648
	v_fmamk_f32 v64, v64, 0x3e38aa3b, v130
	v_exp_f32_e32 v64, v64
	v_add_f32_e32 v74, v61, v74
	v_mov_b32_e32 v165, v17
	s_waitcnt lgkmcnt(2)
	v_mfma_f32_32x32x16_bf16 v[18:33], v[12:15], v[8:11], v[18:33]
	ds_read_b64_tr_b16 v[14:15], v194 offset:27712
	ds_read_b64_tr_b16 v[12:13], v194 offset:26688
	v_cvt_pk_bf16_f32 v11, v72, v73
	v_cvt_pk_bf16_f32 v10, v70, v71
	v_cvt_pk_bf16_f32 v9, v68, v69
	v_cvt_pk_bf16_f32 v8, v66, v67
	s_waitcnt lgkmcnt(2)
	s_nop 0
	v_mfma_f32_32x32x16_bf16 v[34:49], v[4:7], v[8:11], v[34:49]
	v_fmamk_f32 v4, v62, 0x3e38aa3b, v130
	v_exp_f32_e32 v62, v4
	v_fmamk_f32 v4, v63, 0x3e38aa3b, v130
	v_exp_f32_e32 v63, v4
	ds_read_b64_tr_b16 v[4:5], v194 offset:28672
	ds_read_b64_tr_b16 v[6:7], v194 offset:29696
	v_fmac_f32_e32 v130, 0x3e38aa3b, v65
	s_waitcnt lgkmcnt(2)
	v_mfma_f32_32x32x16_bf16 v[18:33], v[12:15], v[8:11], v[18:33]
	ds_read_b64_tr_b16 v[14:15], v194 offset:29760
	ds_read_b64_tr_b16 v[12:13], v194 offset:28736
	v_cvt_pk_bf16_f32 v11, v56, v57
	v_cvt_pk_bf16_f32 v10, v54, v55
	v_cvt_pk_bf16_f32 v9, v52, v53
	v_cvt_pk_bf16_f32 v8, v50, v51
	v_exp_f32_e32 v51, v130
	s_waitcnt lgkmcnt(2)
	v_mfma_f32_32x32x16_bf16 v[34:49], v[4:7], v[8:11], v[34:49]
	v_add_f32_e32 v4, v62, v74
	v_add_f32_e32 v4, v63, v4
	v_add_f32_e32 v50, v64, v4
	ds_read_b64_tr_b16 v[4:5], v194 offset:30720
	ds_read_b64_tr_b16 v[6:7], v194 offset:31744
	v_add_f32_e32 v50, v51, v50
	s_waitcnt lgkmcnt(2)
	v_mfma_f32_32x32x16_bf16 v[18:33], v[12:15], v[8:11], v[18:33]
	ds_read_b64_tr_b16 v[14:15], v194 offset:31808
	ds_read_b64_tr_b16 v[12:13], v194 offset:30784
	v_cvt_pk_bf16_f32 v11, v64, v51
	v_cvt_pk_bf16_f32 v10, v62, v63
	v_cvt_pk_bf16_f32 v9, v60, v61
	v_cvt_pk_bf16_f32 v8, v58, v59
	s_waitcnt lgkmcnt(2)
	s_nop 0
	v_mfma_f32_32x32x16_bf16 v[34:49], v[4:7], v[8:11], v[34:49]
	v_mov_b32_e32 v4, v50
	s_nop 1
	v_permlane32_swap_b32_e32 v50, v4
	v_add_f32_e32 v4, v50, v4
	s_waitcnt lgkmcnt(0)
	v_fmac_f32_e32 v4, v160, v2
	v_mfma_f32_32x32x16_bf16 v[18:33], v[12:15], v[8:11], v[18:33]
	v_mov_b32_e32 v160, v4
